# K-loops: priority lowered after the MFMA-segment barrier instead of before it
# speedup vs baseline: 1.0027x; 1.0027x over previous
; #define PG8_STAGE(bufoff, gbase, voff) do { _Pragma("unroll") for (int _i = 0; _i < 2; ++_i) \
;         __builtin_amdgcn_global_load_lds((const unsigned*)((const char*)(gbase) + (voff)[_i]), (PG8_LAS unsigned*)(lds + (bufoff) + ldsw + _i * 8192), 16, 0, 0); } while (0)
; #define PG8_LDA(dst, b, h) do { _Pragma("unroll") for (int m = 0; m < 4; ++m) _Pragma("unroll") for (int k = 0; k < 2; ++k) dst[m][k] = *(const PG8_LAS bf16x8*)(lds + PG8_SA(b, h) + aoff + m * 2048 + k * 1024); } while (0)
; #define PG8_LDB(dst, b, h) do { _Pragma("unroll") for (int n = 0; n < 2; ++n) _Pragma("unroll") for (int k = 0; k < 2; ++k) dst[n][k] = *(const PG8_LAS bf16x8*)(lds + PG8_SB(b, h) + boff + n * 2048 + k * 1024); } while (0)
; #define PG8_BAR __builtin_amdgcn_s_barrier()
; template <class Epi, class Sched, bool ALIGN_EPI = false, bool SP2 = false>
; __device__ __forceinline__ void gemm_phase(PG8_LAS unsigned char* lds, const Gemm g, const Sched& S, const Epi& E) {
;     ...
;             const bool last = (t == nt - 2);
;             const char* a1 = cA + (size_t)(t + 1) * kstep;
;             const char* a2 = last ? nA : cA + (size_t)(t + 2) * kstep; const char* b2 = last ? nB : cB + (size_t)(t + 2) * kstep;
;             const char* a3 = a2 + kstep; const char* b3 = b2 + kstep;
;             if (last && has_next) S.a_ready(nxt);
;             if constexpr (SP2) {
;             PG8_LDB(B0, 0, 0); PG8_LDB(B1, 0, 1); PG8_SCHED; PG8_LDA(At, 0, 0); PG8_STAGE(PG8_SA(1, 1), a1 + hstep, voffA);
;             PG8_WAIT_V(8); PG8_WAIT_L(0); PG8_BAR; PG8_MMA(0, 0, At, B0); PG8_MMA(0, 1, At, B1); PG8_BAR; PG8_SCHED;
;             PG8_LDA(At, 0, 1); PG8_STAGE(PG8_SB(0, 0), b2, voffB); PG8_STAGE(PG8_SB(0, 1), b2 + hstep, voffB); PG8_STAGE(PG8_SA(0, 0), a2, voffA);
;             PG8_WAIT_V(8); PG8_WAIT_L(0); PG8_BAR; PG8_MMA(1, 0, At, B0); PG8_MMA(1, 1, At, B1); PG8_BAR; PG8_SCHED;
;             PG8_LDB(B0, 1, 0); PG8_LDB(B1, 1, 1); PG8_SCHED; PG8_LDA(At, 1, 0); PG8_STAGE(PG8_SA(0, 1), a2 + hstep, voffA);
;             PG8_WAIT_V(8); PG8_WAIT_L(0); PG8_BAR; PG8_MMA(0, 0, At, B0); PG8_MMA(0, 1, At, B1); PG8_BAR; PG8_SCHED;
;             PG8_LDA(At, 1, 1); PG8_STAGE(PG8_SB(1, 0), b3, voffB); PG8_STAGE(PG8_SB(1, 1), b3 + hstep, voffB); PG8_STAGE(PG8_SA(1, 0), a3, voffA);
;             PG8_WAIT_V(8); PG8_WAIT_L(0); PG8_BAR; PG8_MMA(1, 0, At, B0); PG8_MMA(1, 1, At, B1); PG8_BAR; PG8_SCHED;
.LBB0_123:
	s_add_u32 s8, s6, 0xfff80080
	s_addc_u32 s9, s7, -1
	s_add_i32 s43, 0, 0x10000
	s_cmp_eq_u32 s42, 28
	s_cselect_b32 s23, s15, s9
	s_cselect_b32 s22, s24, s8
	s_cselect_b32 s9, s17, s41
	s_cselect_b32 s8, s25, s40
	s_add_i32 s48, 0, 0x14000
	v_add_u32_e32 v172, s43, v165
	v_add_u32_e32 v188, s48, v165
	ds_read_b128 v[156:159], v172
	ds_read_b128 v[160:163], v172 offset:1024
	ds_read_b128 v[168:171], v172 offset:2048
	ds_read_b128 v[172:175], v172 offset:3072
	ds_read_b128 v[176:179], v188
	ds_read_b128 v[180:183], v188 offset:1024
	ds_read_b128 v[184:187], v188 offset:2048
	ds_read_b128 v[188:191], v188 offset:3072
	v_lshl_add_u64 v[228:229], s[6:7], 0, v[152:153]
	s_add_i32 m0, s31, 0xc000
	ds_read_b128 v[192:195], v167
	ds_read_b128 v[196:199], v167 offset:1024
	ds_read_b128 v[200:203], v167 offset:2048
	ds_read_b128 v[204:207], v167 offset:3072
	ds_read_b128 v[208:211], v167 offset:4096
	ds_read_b128 v[212:215], v167 offset:5120
	ds_read_b128 v[216:219], v167 offset:6144
	ds_read_b128 v[224:227], v167 offset:7168
	global_load_lds_dwordx4 v[228:229], off
	s_add_i32 m0, s31, 0xe000
	v_lshl_add_u64 v[228:229], s[6:7], 0, v[154:155]
	global_load_lds_dwordx4 v[228:229], off
	s_waitcnt vmcnt(8) lgkmcnt(0)
	s_setprio 1
	s_barrier
	v_mfma_f32_16x16x32_bf16 v[144:147], v[156:159], v[192:195], v[144:147]
	v_mfma_f32_16x16x32_bf16 v[122:125], v[168:171], v[192:195], v[122:125]
	v_mfma_f32_16x16x32_bf16 v[110:113], v[156:159], v[200:203], v[110:113]
	v_mfma_f32_16x16x32_bf16 v[106:109], v[168:171], v[200:203], v[106:109]
	v_mfma_f32_16x16x32_bf16 v[94:97], v[156:159], v[208:211], v[94:97]
	v_mfma_f32_16x16x32_bf16 v[90:93], v[168:171], v[208:211], v[90:93]
	v_mfma_f32_16x16x32_bf16 v[78:81], v[156:159], v[216:219], v[78:81]
	v_mfma_f32_16x16x32_bf16 v[74:77], v[168:171], v[216:219], v[74:77]
	v_mfma_f32_16x16x32_bf16 v[144:147], v[160:163], v[196:199], v[144:147]
	v_mfma_f32_16x16x32_bf16 v[122:125], v[172:175], v[196:199], v[122:125]
	v_mfma_f32_16x16x32_bf16 v[110:113], v[160:163], v[204:207], v[110:113]
	v_mfma_f32_16x16x32_bf16 v[106:109], v[172:175], v[204:207], v[106:109]
	v_mfma_f32_16x16x32_bf16 v[94:97], v[160:163], v[212:215], v[94:97]
	v_mfma_f32_16x16x32_bf16 v[90:93], v[172:175], v[212:215], v[90:93]
	v_mfma_f32_16x16x32_bf16 v[78:81], v[160:163], v[224:227], v[78:81]
	v_mfma_f32_16x16x32_bf16 v[74:77], v[172:175], v[224:227], v[74:77]
	v_mfma_f32_16x16x32_bf16 v[118:121], v[176:179], v[192:195], v[118:121]
	v_mfma_f32_16x16x32_bf16 v[114:117], v[184:187], v[192:195], v[114:117]
	v_mfma_f32_16x16x32_bf16 v[102:105], v[176:179], v[200:203], v[102:105]
	v_mfma_f32_16x16x32_bf16 v[98:101], v[184:187], v[200:203], v[98:101]
	v_mfma_f32_16x16x32_bf16 v[86:89], v[176:179], v[208:211], v[86:89]
	v_mfma_f32_16x16x32_bf16 v[82:85], v[184:187], v[208:211], v[82:85]
	v_mfma_f32_16x16x32_bf16 v[70:73], v[176:179], v[216:219], v[70:73]
	v_mfma_f32_16x16x32_bf16 v[66:69], v[184:187], v[216:219], v[66:69]
	v_mfma_f32_16x16x32_bf16 v[118:121], v[180:183], v[196:199], v[118:121]
	v_mfma_f32_16x16x32_bf16 v[114:117], v[188:191], v[196:199], v[114:117]
	v_mfma_f32_16x16x32_bf16 v[102:105], v[180:183], v[204:207], v[102:105]
	v_mfma_f32_16x16x32_bf16 v[98:101], v[188:191], v[204:207], v[98:101]
	v_mfma_f32_16x16x32_bf16 v[86:89], v[180:183], v[212:215], v[86:89]
	v_mfma_f32_16x16x32_bf16 v[82:85], v[188:191], v[212:215], v[82:85]
	v_mfma_f32_16x16x32_bf16 v[70:73], v[180:183], v[224:227], v[70:73]
	v_mfma_f32_16x16x32_bf16 v[66:69], v[188:191], v[224:227], v[66:69]
	s_barrier
	s_setprio 0
	s_add_i32 s43, s43, s30
	v_lshl_add_u64 v[228:229], s[8:9], 0, v[0:1]
	s_mov_b32 m0, s43
	ds_read_b128 v[192:195], v167 offset:16384
	ds_read_b128 v[196:199], v167 offset:17408
	ds_read_b128 v[200:203], v167 offset:18432
	ds_read_b128 v[204:207], v167 offset:19456
	ds_read_b128 v[208:211], v167 offset:20480
	ds_read_b128 v[212:215], v167 offset:21504
	ds_read_b128 v[216:219], v167 offset:22528
	ds_read_b128 v[224:227], v167 offset:23552
	global_load_lds_dwordx4 v[228:229], off
	s_add_i32 m0, s43, 0x2000
	s_add_u32 s82, s8, 0x80000
	v_lshl_add_u64 v[230:231], s[8:9], 0, v[126:127]
	s_addc_u32 s83, s9, 0
	s_add_i32 s43, s48, s30
	global_load_lds_dwordx4 v[230:231], off
	v_lshl_add_u64 v[232:233], s[82:83], 0, v[0:1]
	s_mov_b32 m0, s43
	v_lshl_add_u64 v[244:245], s[22:23], 0, v[148:149]
	global_load_lds_dwordx4 v[232:233], off
	s_add_i32 m0, s43, 0x2000
	v_lshl_add_u64 v[232:233], s[82:83], 0, v[126:127]
	global_load_lds_dwordx4 v[232:233], off
	s_mov_b32 m0, s31
	v_lshl_add_u64 v[232:233], s[22:23], 0, v[150:151]
	global_load_lds_dwordx4 v[232:233], off
	s_mov_b32 m0, s34
	s_nop 0
	global_load_lds_dwordx4 v[244:245], off
	s_waitcnt vmcnt(8) lgkmcnt(0)
	s_setprio 1
	s_barrier
; #define PG8_STAGE(bufoff, gbase, voff) do { _Pragma("unroll") for (int _i = 0; _i < 2; ++_i) \
;         __builtin_amdgcn_global_load_lds((const unsigned*)((const char*)(gbase) + (voff)[_i]), (PG8_LAS unsigned*)(lds + (bufoff) + ldsw + _i * 8192), 16, 0, 0); } while (0)
; #define PG8_LDA(dst, b, h) do { _Pragma("unroll") for (int m = 0; m < 4; ++m) _Pragma("unroll") for (int k = 0; k < 2; ++k) dst[m][k] = *(const PG8_LAS bf16x8*)(lds + PG8_SA(b, h) + aoff + m * 2048 + k * 1024); } while (0)
; #define PG8_LDB(dst, b, h) do { _Pragma("unroll") for (int n = 0; n < 2; ++n) _Pragma("unroll") for (int k = 0; k < 2; ++k) dst[n][k] = *(const PG8_LAS bf16x8*)(lds + PG8_SB(b, h) + boff + n * 2048 + k * 1024); } while (0)
; #define PG8_MMA(ai, bj, At, Bt) do { __builtin_amdgcn_s_setprio(1); _Pragma("unroll") for (int m = 0; m < 4; ++m) _Pragma("unroll") for (int n = 0; n < 2; ++n) _Pragma("unroll") for (int k = 0; k < 2; ++k) \
;         acc[ai][bj][m][n] = __builtin_amdgcn_mfma_f32_16x16x32_bf16(Bt[n][k], At[m][k], acc[ai][bj][m][n], 0, 0, 0); __builtin_amdgcn_s_setprio(0); } while (0)
; #define PG8_WAIT_V(n) asm volatile("s_waitcnt vmcnt(" #n ")" ::: "memory")
; #define PG8_WAIT_L(n) asm volatile("s_waitcnt lgkmcnt(" #n ")" ::: "memory")
; #define PG8_BAR __builtin_amdgcn_s_barrier()
; #define PG8_SCHED __builtin_amdgcn_sched_barrier(0)
; template <class Epi, class Sched, bool ALIGN_EPI = false, bool SP2 = false>
; __device__ __forceinline__ void gemm_phase(PG8_LAS unsigned char* lds, const Gemm g, const Sched& S, const Epi& E) {
;     ...
;             PG8_WAIT_V(8); PG8_WAIT_L(0); PG8_BAR; PG8_MMA(0, 0, At, B0); PG8_MMA(0, 1, At, B1); PG8_BAR; PG8_SCHED;
;             PG8_LDA(At, 0, 1); PG8_STAGE(PG8_SB(0, 0), b2, voffB); PG8_STAGE(PG8_SB(0, 1), b2 + hstep, voffB); PG8_STAGE(PG8_SA(0, 0), a2, voffA);
;             PG8_WAIT_V(8); PG8_WAIT_L(0); PG8_BAR; PG8_MMA(1, 0, At, B0); PG8_MMA(1, 1, At, B1); PG8_BAR; PG8_SCHED;
;             PG8_LDB(B0, 1, 0); PG8_LDB(B1, 1, 1); PG8_SCHED; PG8_LDA(At, 1, 0); PG8_STAGE(PG8_SA(0, 1), a2 + hstep, voffA);
;             PG8_WAIT_V(8); PG8_WAIT_L(0); PG8_BAR; PG8_MMA(0, 0, At, B0); PG8_MMA(0, 1, At, B1); PG8_BAR; PG8_SCHED;
	v_mfma_f32_16x16x32_bf16 v[62:65], v[156:159], v[192:195], v[62:65]
	v_mfma_f32_16x16x32_bf16 v[58:61], v[168:171], v[192:195], v[58:61]
	v_mfma_f32_16x16x32_bf16 v[46:49], v[156:159], v[200:203], v[46:49]
	v_mfma_f32_16x16x32_bf16 v[42:45], v[168:171], v[200:203], v[42:45]
	v_mfma_f32_16x16x32_bf16 v[30:33], v[156:159], v[208:211], v[30:33]
	v_mfma_f32_16x16x32_bf16 v[26:29], v[168:171], v[208:211], v[26:29]
	v_mfma_f32_16x16x32_bf16 v[14:17], v[156:159], v[216:219], v[14:17]
	v_mfma_f32_16x16x32_bf16 v[10:13], v[168:171], v[216:219], v[10:13]
	v_mfma_f32_16x16x32_bf16 v[62:65], v[160:163], v[196:199], v[62:65]
	v_mfma_f32_16x16x32_bf16 v[58:61], v[172:175], v[196:199], v[58:61]
	v_mfma_f32_16x16x32_bf16 v[46:49], v[160:163], v[204:207], v[46:49]
	v_mfma_f32_16x16x32_bf16 v[42:45], v[172:175], v[204:207], v[42:45]
	v_mfma_f32_16x16x32_bf16 v[30:33], v[160:163], v[212:215], v[30:33]
	v_mfma_f32_16x16x32_bf16 v[26:29], v[172:175], v[212:215], v[26:29]
	v_mfma_f32_16x16x32_bf16 v[14:17], v[160:163], v[224:227], v[14:17]
	v_mfma_f32_16x16x32_bf16 v[10:13], v[172:175], v[224:227], v[10:13]
	v_mfma_f32_16x16x32_bf16 v[54:57], v[176:179], v[192:195], v[54:57]
	v_mfma_f32_16x16x32_bf16 v[50:53], v[184:187], v[192:195], v[50:53]
	v_mfma_f32_16x16x32_bf16 v[38:41], v[176:179], v[200:203], v[38:41]
	v_mfma_f32_16x16x32_bf16 v[34:37], v[184:187], v[200:203], v[34:37]
	v_mfma_f32_16x16x32_bf16 v[22:25], v[176:179], v[208:211], v[22:25]
	v_mfma_f32_16x16x32_bf16 v[18:21], v[184:187], v[208:211], v[18:21]
	v_mfma_f32_16x16x32_bf16 v[6:9], v[176:179], v[216:219], v[6:9]
	v_mfma_f32_16x16x32_bf16 v[2:5], v[184:187], v[216:219], v[2:5]
	v_mfma_f32_16x16x32_bf16 v[54:57], v[180:183], v[196:199], v[54:57]
	v_mfma_f32_16x16x32_bf16 v[50:53], v[188:191], v[196:199], v[50:53]
	v_mfma_f32_16x16x32_bf16 v[38:41], v[180:183], v[204:207], v[38:41]
	v_mfma_f32_16x16x32_bf16 v[34:37], v[188:191], v[204:207], v[34:37]
	v_mfma_f32_16x16x32_bf16 v[22:25], v[180:183], v[212:215], v[22:25]
	v_mfma_f32_16x16x32_bf16 v[18:21], v[188:191], v[212:215], v[18:21]
	v_mfma_f32_16x16x32_bf16 v[6:9], v[180:183], v[224:227], v[6:9]
	v_mfma_f32_16x16x32_bf16 v[2:5], v[188:191], v[224:227], v[2:5]
	s_barrier
	s_setprio 0
	s_add_i32 s43, 0, 0x18000
	s_add_i32 s48, 0, 0x1c000
	v_add_u32_e32 v172, s43, v165
	v_add_u32_e32 v188, s48, v165
	ds_read_b128 v[156:159], v172
	ds_read_b128 v[160:163], v172 offset:1024
	ds_read_b128 v[168:171], v172 offset:2048
	ds_read_b128 v[172:175], v172 offset:3072
	ds_read_b128 v[176:179], v188
	ds_read_b128 v[180:183], v188 offset:1024
	ds_read_b128 v[184:187], v188 offset:2048
	ds_read_b128 v[188:191], v188 offset:3072
	s_add_u32 s22, s22, 0x80000
	s_addc_u32 s23, s23, 0
	s_mov_b32 m0, s35
	v_lshl_add_u64 v[246:247], s[22:23], 0, v[150:151]
	ds_read_b128 v[192:195], v167 offset:32768
	ds_read_b128 v[196:199], v167 offset:33792
	ds_read_b128 v[200:203], v167 offset:34816
	ds_read_b128 v[204:207], v167 offset:35840
	ds_read_b128 v[208:211], v167 offset:36864
	ds_read_b128 v[212:215], v167 offset:37888
	ds_read_b128 v[216:219], v167 offset:38912
	ds_read_b128 v[224:227], v167 offset:39936
	global_load_lds_dwordx4 v[246:247], off
	s_mov_b32 m0, s36
	v_lshl_add_u64 v[246:247], s[22:23], 0, v[148:149]
	global_load_lds_dwordx4 v[246:247], off
	s_waitcnt vmcnt(8) lgkmcnt(0)
	s_setprio 1
	s_barrier
	v_mfma_f32_16x16x32_bf16 v[144:147], v[156:159], v[192:195], v[144:147]
	v_mfma_f32_16x16x32_bf16 v[122:125], v[168:171], v[192:195], v[122:125]
	v_mfma_f32_16x16x32_bf16 v[110:113], v[156:159], v[200:203], v[110:113]
	v_mfma_f32_16x16x32_bf16 v[106:109], v[168:171], v[200:203], v[106:109]
	v_mfma_f32_16x16x32_bf16 v[94:97], v[156:159], v[208:211], v[94:97]
	v_mfma_f32_16x16x32_bf16 v[90:93], v[168:171], v[208:211], v[90:93]
	v_mfma_f32_16x16x32_bf16 v[78:81], v[156:159], v[216:219], v[78:81]
	v_mfma_f32_16x16x32_bf16 v[74:77], v[168:171], v[216:219], v[74:77]
	v_mfma_f32_16x16x32_bf16 v[144:147], v[160:163], v[196:199], v[144:147]
	v_mfma_f32_16x16x32_bf16 v[122:125], v[172:175], v[196:199], v[122:125]
	v_mfma_f32_16x16x32_bf16 v[110:113], v[160:163], v[204:207], v[110:113]
	v_mfma_f32_16x16x32_bf16 v[106:109], v[172:175], v[204:207], v[106:109]
	v_mfma_f32_16x16x32_bf16 v[94:97], v[160:163], v[212:215], v[94:97]
	v_mfma_f32_16x16x32_bf16 v[90:93], v[172:175], v[212:215], v[90:93]
	v_mfma_f32_16x16x32_bf16 v[78:81], v[160:163], v[224:227], v[78:81]
	v_mfma_f32_16x16x32_bf16 v[74:77], v[172:175], v[224:227], v[74:77]
	v_mfma_f32_16x16x32_bf16 v[118:121], v[176:179], v[192:195], v[118:121]
	v_mfma_f32_16x16x32_bf16 v[114:117], v[184:187], v[192:195], v[114:117]
	v_mfma_f32_16x16x32_bf16 v[102:105], v[176:179], v[200:203], v[102:105]
	v_mfma_f32_16x16x32_bf16 v[98:101], v[184:187], v[200:203], v[98:101]
	v_mfma_f32_16x16x32_bf16 v[86:89], v[176:179], v[208:211], v[86:89]
	v_mfma_f32_16x16x32_bf16 v[82:85], v[184:187], v[208:211], v[82:85]
	v_mfma_f32_16x16x32_bf16 v[70:73], v[176:179], v[216:219], v[70:73]
	v_mfma_f32_16x16x32_bf16 v[66:69], v[184:187], v[216:219], v[66:69]
	v_mfma_f32_16x16x32_bf16 v[118:121], v[180:183], v[196:199], v[118:121]
	v_mfma_f32_16x16x32_bf16 v[114:117], v[188:191], v[196:199], v[114:117]
	v_mfma_f32_16x16x32_bf16 v[102:105], v[180:183], v[204:207], v[102:105]
	v_mfma_f32_16x16x32_bf16 v[98:101], v[188:191], v[204:207], v[98:101]
	v_mfma_f32_16x16x32_bf16 v[86:89], v[180:183], v[212:215], v[86:89]
	v_mfma_f32_16x16x32_bf16 v[82:85], v[188:191], v[212:215], v[82:85]
	v_mfma_f32_16x16x32_bf16 v[70:73], v[180:183], v[224:227], v[70:73]
	v_mfma_f32_16x16x32_bf16 v[66:69], v[188:191], v[224:227], v[66:69]
	s_barrier
; #define PG8_STAGE(bufoff, gbase, voff) do { _Pragma("unroll") for (int _i = 0; _i < 2; ++_i) \
;         __builtin_amdgcn_global_load_lds((const unsigned*)((const char*)(gbase) + (voff)[_i]), (PG8_LAS unsigned*)(lds + (bufoff) + ldsw + _i * 8192), 16, 0, 0); } while (0)
; #define PG8_LDA(dst, b, h) do { _Pragma("unroll") for (int m = 0; m < 4; ++m) _Pragma("unroll") for (int k = 0; k < 2; ++k) dst[m][k] = *(const PG8_LAS bf16x8*)(lds + PG8_SA(b, h) + aoff + m * 2048 + k * 1024); } while (0)
; #define PG8_WAIT_V(n) asm volatile("s_waitcnt vmcnt(" #n ")" ::: "memory")
; template <class Epi, class Sched, bool ALIGN_EPI = false, bool SP2 = false>
; __device__ __forceinline__ void gemm_phase(PG8_LAS unsigned char* lds, const Gemm g, const Sched& S, const Epi& E) {
;     ...
;         for (int t = 0; t < nt; t += 2) {
;             if constexpr (Epi::HAS_MID) { if (t == Epi::MID0 || t == Epi::MID1) E.mid(acc, cur, wr, wc, fr, fq, t == Epi::MID0 ? 0 : 1); }
;             const bool last = (t == nt - 2);
;             const char* a1 = cA + (size_t)(t + 1) * kstep;
;             const char* a2 = last ? nA : cA + (size_t)(t + 2) * kstep; const char* b2 = last ? nB : cB + (size_t)(t + 2) * kstep;
;             const char* a3 = a2 + kstep; const char* b3 = b2 + kstep;
;             if (last && has_next) S.a_ready(nxt);
;             if constexpr (SP2) {
;             PG8_LDB(B0, 0, 0); PG8_LDB(B1, 0, 1); PG8_SCHED; PG8_LDA(At, 0, 0); PG8_STAGE(PG8_SA(1, 1), a1 + hstep, voffA);
;             PG8_WAIT_V(8); PG8_WAIT_L(0); PG8_BAR; PG8_MMA(0, 0, At, B0); PG8_MMA(0, 1, At, B1); PG8_BAR; PG8_SCHED;
;             PG8_LDA(At, 0, 1); PG8_STAGE(PG8_SB(0, 0), b2, voffB); PG8_STAGE(PG8_SB(0, 1), b2 + hstep, voffB); PG8_STAGE(PG8_SA(0, 0), a2, voffA);
;             PG8_WAIT_V(8); PG8_WAIT_L(0); PG8_BAR; PG8_MMA(1, 0, At, B0); PG8_MMA(1, 1, At, B1); PG8_BAR; PG8_SCHED;
;             PG8_LDB(B0, 1, 0); PG8_LDB(B1, 1, 1); PG8_SCHED; PG8_LDA(At, 1, 0); PG8_STAGE(PG8_SA(0, 1), a2 + hstep, voffA);
;             PG8_WAIT_V(8); PG8_WAIT_L(0); PG8_BAR; PG8_MMA(0, 0, At, B0); PG8_MMA(0, 1, At, B1); PG8_BAR; PG8_SCHED;
;             PG8_LDA(At, 1, 1); PG8_STAGE(PG8_SB(1, 0), b3, voffB); PG8_STAGE(PG8_SB(1, 1), b3 + hstep, voffB); PG8_STAGE(PG8_SA(1, 0), a3, voffA);
;             PG8_WAIT_V(8); PG8_WAIT_L(0); PG8_BAR; PG8_MMA(1, 0, At, B0); PG8_MMA(1, 1, At, B1); PG8_BAR; PG8_SCHED;
	s_setprio 0
	s_add_i32 s22, s43, s30
	v_lshl_add_u64 v[228:229], v[228:229], 0, s[64:65]
	s_mov_b32 m0, s22
	ds_read_b128 v[192:195], v167 offset:49152
	ds_read_b128 v[196:199], v167 offset:50176
	ds_read_b128 v[200:203], v167 offset:51200
	ds_read_b128 v[204:207], v167 offset:52224
	ds_read_b128 v[208:211], v167 offset:53248
	ds_read_b128 v[212:215], v167 offset:54272
	ds_read_b128 v[216:219], v167 offset:55296
	ds_read_b128 v[224:227], v167 offset:56320
	global_load_lds_dwordx4 v[228:229], off
	s_add_i32 m0, s22, 0x2000
	s_add_u32 s8, s8, 0x80080
	v_lshl_add_u64 v[228:229], v[230:231], 0, s[64:65]
	s_addc_u32 s9, s9, 0
	s_add_i32 s22, s48, s30
	global_load_lds_dwordx4 v[228:229], off
	s_mov_b32 m0, s22
	v_lshl_add_u64 v[228:229], s[8:9], 0, v[0:1]
	global_load_lds_dwordx4 v[228:229], off
	s_add_i32 m0, s22, 0x2000
	v_lshl_add_u64 v[228:229], s[8:9], 0, v[126:127]
	global_load_lds_dwordx4 v[228:229], off
	s_mov_b32 m0, s37
	v_lshl_add_u64 v[228:229], v[232:233], 0, s[64:65]
	global_load_lds_dwordx4 v[228:229], off
	s_mov_b32 m0, s76
	v_lshl_add_u64 v[228:229], v[244:245], 0, s[64:65]
	global_load_lds_dwordx4 v[228:229], off
	s_waitcnt vmcnt(8) lgkmcnt(0)
	s_setprio 1
	s_barrier
	v_mfma_f32_16x16x32_bf16 v[62:65], v[156:159], v[192:195], v[62:65]
	v_mfma_f32_16x16x32_bf16 v[58:61], v[168:171], v[192:195], v[58:61]
	v_mfma_f32_16x16x32_bf16 v[46:49], v[156:159], v[200:203], v[46:49]
	v_mfma_f32_16x16x32_bf16 v[42:45], v[168:171], v[200:203], v[42:45]
	v_mfma_f32_16x16x32_bf16 v[30:33], v[156:159], v[208:211], v[30:33]
	v_mfma_f32_16x16x32_bf16 v[26:29], v[168:171], v[208:211], v[26:29]
	v_mfma_f32_16x16x32_bf16 v[14:17], v[156:159], v[216:219], v[14:17]
	v_mfma_f32_16x16x32_bf16 v[10:13], v[168:171], v[216:219], v[10:13]
	v_mfma_f32_16x16x32_bf16 v[62:65], v[160:163], v[196:199], v[62:65]
	v_mfma_f32_16x16x32_bf16 v[58:61], v[172:175], v[196:199], v[58:61]
	v_mfma_f32_16x16x32_bf16 v[46:49], v[160:163], v[204:207], v[46:49]
	v_mfma_f32_16x16x32_bf16 v[42:45], v[172:175], v[204:207], v[42:45]
	v_mfma_f32_16x16x32_bf16 v[30:33], v[160:163], v[212:215], v[30:33]
	v_mfma_f32_16x16x32_bf16 v[26:29], v[172:175], v[212:215], v[26:29]
	v_mfma_f32_16x16x32_bf16 v[14:17], v[160:163], v[224:227], v[14:17]
	v_mfma_f32_16x16x32_bf16 v[10:13], v[172:175], v[224:227], v[10:13]
	v_mfma_f32_16x16x32_bf16 v[54:57], v[176:179], v[192:195], v[54:57]
	v_mfma_f32_16x16x32_bf16 v[50:53], v[184:187], v[192:195], v[50:53]
	v_mfma_f32_16x16x32_bf16 v[38:41], v[176:179], v[200:203], v[38:41]
	v_mfma_f32_16x16x32_bf16 v[34:37], v[184:187], v[200:203], v[34:37]
	v_mfma_f32_16x16x32_bf16 v[22:25], v[176:179], v[208:211], v[22:25]
	v_mfma_f32_16x16x32_bf16 v[18:21], v[184:187], v[208:211], v[18:21]
	v_mfma_f32_16x16x32_bf16 v[6:9], v[176:179], v[216:219], v[6:9]
	v_mfma_f32_16x16x32_bf16 v[2:5], v[184:187], v[216:219], v[2:5]
	v_mfma_f32_16x16x32_bf16 v[54:57], v[180:183], v[196:199], v[54:57]
	v_mfma_f32_16x16x32_bf16 v[50:53], v[188:191], v[196:199], v[50:53]
	v_mfma_f32_16x16x32_bf16 v[38:41], v[180:183], v[204:207], v[38:41]
	v_mfma_f32_16x16x32_bf16 v[34:37], v[188:191], v[204:207], v[34:37]
	v_mfma_f32_16x16x32_bf16 v[22:25], v[180:183], v[212:215], v[22:25]
	v_mfma_f32_16x16x32_bf16 v[18:21], v[188:191], v[212:215], v[18:21]
	v_mfma_f32_16x16x32_bf16 v[6:9], v[180:183], v[224:227], v[6:9]
	v_mfma_f32_16x16x32_bf16 v[2:5], v[188:191], v[224:227], v[2:5]
	s_barrier
	s_setprio 0
	s_add_i32 s42, s42, 2
	s_add_u32 s6, s6, 0x100
	s_addc_u32 s7, s7, 0
	s_add_u32 s40, s40, 0x100
	s_addc_u32 s41, s41, 0
	s_cmp_gt_u32 s42, 29
	s_cbranch_scc0 .LBB0_123
	s_and_b64 vcc, exec, s[12:13]
	s_cbranch_vccz .LBB0_126
	s_barrier

; #define PG8_STAGE(bufoff, gbase, voff) do { _Pragma("unroll") for (int _i = 0; _i < 2; ++_i) \
;         __builtin_amdgcn_global_load_lds((const unsigned*)((const char*)(gbase) + (voff)[_i]), (PG8_LAS unsigned*)(lds + (bufoff) + ldsw + _i * 8192), 16, 0, 0); } while (0)
; #define PG8_LDA(dst, b, h) do { _Pragma("unroll") for (int m = 0; m < 4; ++m) _Pragma("unroll") for (int k = 0; k < 2; ++k) dst[m][k] = *(const PG8_LAS bf16x8*)(lds + PG8_SA(b, h) + aoff + m * 2048 + k * 1024); } while (0)
; #define PG8_LDB(dst, b, h) do { _Pragma("unroll") for (int n = 0; n < 2; ++n) _Pragma("unroll") for (int k = 0; k < 2; ++k) dst[n][k] = *(const PG8_LAS bf16x8*)(lds + PG8_SB(b, h) + boff + n * 2048 + k * 1024); } while (0)
; #define PG8_BAR __builtin_amdgcn_s_barrier()
; template <class Epi, class Sched, bool ALIGN_EPI = false, bool SP2 = false>
; __device__ __forceinline__ void gemm_phase(PG8_LAS unsigned char* lds, const Gemm g, const Sched& S, const Epi& E) {
;     ...
;             const bool last = (t == nt - 2);
;             const char* a1 = cA + (size_t)(t + 1) * kstep;
;             const char* a2 = last ? nA : cA + (size_t)(t + 2) * kstep; const char* b2 = last ? nB : cB + (size_t)(t + 2) * kstep;
;             const char* a3 = a2 + kstep; const char* b3 = b2 + kstep;
;             if (last && has_next) S.a_ready(nxt);
;             if constexpr (SP2) {
;             PG8_LDB(B0, 0, 0); PG8_LDB(B1, 0, 1); PG8_SCHED; PG8_LDA(At, 0, 0); PG8_STAGE(PG8_SA(1, 1), a1 + hstep, voffA);
;             PG8_WAIT_V(8); PG8_WAIT_L(0); PG8_BAR; PG8_MMA(0, 0, At, B0); PG8_MMA(0, 1, At, B1); PG8_BAR; PG8_SCHED;
;             PG8_LDA(At, 0, 1); PG8_STAGE(PG8_SB(0, 0), b2, voffB); PG8_STAGE(PG8_SB(0, 1), b2 + hstep, voffB); PG8_STAGE(PG8_SA(0, 0), a2, voffA);
;             PG8_WAIT_V(8); PG8_WAIT_L(0); PG8_BAR; PG8_MMA(1, 0, At, B0); PG8_MMA(1, 1, At, B1); PG8_BAR; PG8_SCHED;
;             PG8_LDB(B0, 1, 0); PG8_LDB(B1, 1, 1); PG8_SCHED; PG8_LDA(At, 1, 0); PG8_STAGE(PG8_SA(0, 1), a2 + hstep, voffA);
;             PG8_WAIT_V(8); PG8_WAIT_L(0); PG8_BAR; PG8_MMA(0, 0, At, B0); PG8_MMA(0, 1, At, B1); PG8_BAR; PG8_SCHED;
;             PG8_LDA(At, 1, 1); PG8_STAGE(PG8_SB(1, 0), b3, voffB); PG8_STAGE(PG8_SB(1, 1), b3 + hstep, voffB); PG8_STAGE(PG8_SA(1, 0), a3, voffA);
;             PG8_WAIT_V(8); PG8_WAIT_L(0); PG8_BAR; PG8_MMA(1, 0, At, B0); PG8_MMA(1, 1, At, B1); PG8_BAR; PG8_SCHED;
.LBB0_307:
	s_add_u32 s4, s42, s0
	s_addc_u32 s5, s43, s1
	s_add_u32 s4, s4, 0x2cc00100
	s_addc_u32 s5, s5, 0
	s_add_u32 s20, s48, s0
	s_addc_u32 s21, s67, s1
	s_add_i32 s22, 0, 0x10000
	s_cmpk_eq_i32 s0, 0xf00
	s_cselect_b32 s7, s55, s5
	s_cselect_b32 s6, s54, s4
	s_cselect_b32 s5, s53, s21
	s_cselect_b32 s4, s52, s20
	s_add_i32 s23, 0, 0x14000
	v_add_u32_e32 v172, s22, v158
	v_add_u32_e32 v188, s23, v158
	ds_read_b128 v[160:163], v172
	ds_read_b128 v[164:167], v172 offset:1024
	ds_read_b128 v[168:171], v172 offset:2048
	ds_read_b128 v[172:175], v172 offset:3072
	ds_read_b128 v[176:179], v188
	ds_read_b128 v[180:183], v188 offset:1024
	ds_read_b128 v[184:187], v188 offset:2048
	ds_read_b128 v[188:191], v188 offset:3072
	v_lshl_add_u64 v[228:229], v[152:153], 0, s[0:1]
	s_add_i32 m0, s12, 0xc000
	ds_read_b128 v[192:195], v159
	ds_read_b128 v[196:199], v159 offset:1024
	ds_read_b128 v[200:203], v159 offset:2048
	ds_read_b128 v[204:207], v159 offset:3072
	ds_read_b128 v[208:211], v159 offset:4096
	ds_read_b128 v[212:215], v159 offset:5120
	ds_read_b128 v[216:219], v159 offset:6144
	ds_read_b128 v[224:227], v159 offset:7168
	global_load_lds_dwordx4 v[228:229], off
	s_add_i32 m0, s12, 0xe000
	v_lshl_add_u64 v[228:229], v[154:155], 0, s[0:1]
	global_load_lds_dwordx4 v[228:229], off
	s_waitcnt vmcnt(8) lgkmcnt(0)
	s_setprio 1
	s_barrier
	v_mfma_f32_16x16x32_bf16 v[144:147], v[160:163], v[192:195], v[144:147]
	v_mfma_f32_16x16x32_bf16 v[122:125], v[168:171], v[192:195], v[122:125]
	v_mfma_f32_16x16x32_bf16 v[118:121], v[160:163], v[200:203], v[118:121]
	v_mfma_f32_16x16x32_bf16 v[114:117], v[168:171], v[200:203], v[114:117]
	v_mfma_f32_16x16x32_bf16 v[102:105], v[160:163], v[208:211], v[102:105]
	v_mfma_f32_16x16x32_bf16 v[98:101], v[168:171], v[208:211], v[98:101]
	v_mfma_f32_16x16x32_bf16 v[86:89], v[160:163], v[216:219], v[86:89]
	v_mfma_f32_16x16x32_bf16 v[82:85], v[168:171], v[216:219], v[82:85]
	v_mfma_f32_16x16x32_bf16 v[144:147], v[164:167], v[196:199], v[144:147]
	v_mfma_f32_16x16x32_bf16 v[122:125], v[172:175], v[196:199], v[122:125]
	v_mfma_f32_16x16x32_bf16 v[118:121], v[164:167], v[204:207], v[118:121]
	v_mfma_f32_16x16x32_bf16 v[114:117], v[172:175], v[204:207], v[114:117]
	v_mfma_f32_16x16x32_bf16 v[102:105], v[164:167], v[212:215], v[102:105]
	v_mfma_f32_16x16x32_bf16 v[98:101], v[172:175], v[212:215], v[98:101]
	v_mfma_f32_16x16x32_bf16 v[86:89], v[164:167], v[224:227], v[86:89]
	v_mfma_f32_16x16x32_bf16 v[82:85], v[172:175], v[224:227], v[82:85]
	v_mfma_f32_16x16x32_bf16 v[110:113], v[176:179], v[192:195], v[110:113]
	v_mfma_f32_16x16x32_bf16 v[106:109], v[184:187], v[192:195], v[106:109]
	v_mfma_f32_16x16x32_bf16 v[94:97], v[176:179], v[200:203], v[94:97]
	v_mfma_f32_16x16x32_bf16 v[90:93], v[184:187], v[200:203], v[90:93]
	v_mfma_f32_16x16x32_bf16 v[78:81], v[176:179], v[208:211], v[78:81]
	v_mfma_f32_16x16x32_bf16 v[74:77], v[184:187], v[208:211], v[74:77]
	v_mfma_f32_16x16x32_bf16 v[70:73], v[176:179], v[216:219], v[70:73]
	v_mfma_f32_16x16x32_bf16 v[66:69], v[184:187], v[216:219], v[66:69]
	v_mfma_f32_16x16x32_bf16 v[110:113], v[180:183], v[196:199], v[110:113]
	v_mfma_f32_16x16x32_bf16 v[106:109], v[188:191], v[196:199], v[106:109]
	v_mfma_f32_16x16x32_bf16 v[94:97], v[180:183], v[204:207], v[94:97]
	v_mfma_f32_16x16x32_bf16 v[90:93], v[188:191], v[204:207], v[90:93]
	v_mfma_f32_16x16x32_bf16 v[78:81], v[180:183], v[212:215], v[78:81]
	v_mfma_f32_16x16x32_bf16 v[74:77], v[188:191], v[212:215], v[74:77]
	v_mfma_f32_16x16x32_bf16 v[70:73], v[180:183], v[224:227], v[70:73]
	v_mfma_f32_16x16x32_bf16 v[66:69], v[188:191], v[224:227], v[66:69]
	s_barrier
	s_setprio 0
	s_add_i32 s20, s22, s9
	v_lshl_add_u64 v[228:229], s[4:5], 0, v[0:1]
	s_mov_b32 m0, s20
	ds_read_b128 v[192:195], v159 offset:16384
	ds_read_b128 v[196:199], v159 offset:17408
	ds_read_b128 v[200:203], v159 offset:18432
	ds_read_b128 v[204:207], v159 offset:19456
	ds_read_b128 v[208:211], v159 offset:20480
	ds_read_b128 v[212:215], v159 offset:21504
	ds_read_b128 v[216:219], v159 offset:22528
	ds_read_b128 v[224:227], v159 offset:23552
	global_load_lds_dwordx4 v[228:229], off
	s_add_i32 m0, s20, 0x2000
	s_add_u32 s20, s4, 0x80000
	v_lshl_add_u64 v[230:231], s[4:5], 0, v[126:127]
	s_addc_u32 s21, s5, 0
	s_add_i32 s22, s23, s9
	global_load_lds_dwordx4 v[230:231], off
	v_lshl_add_u64 v[232:233], s[20:21], 0, v[0:1]
	s_mov_b32 m0, s22
	v_lshl_add_u64 v[244:245], s[6:7], 0, v[148:149]
	global_load_lds_dwordx4 v[232:233], off
	s_add_i32 m0, s22, 0x2000
	v_lshl_add_u64 v[232:233], s[20:21], 0, v[126:127]
	global_load_lds_dwordx4 v[232:233], off
	s_mov_b32 m0, s12
	v_lshl_add_u64 v[232:233], s[6:7], 0, v[150:151]
	global_load_lds_dwordx4 v[232:233], off
	s_mov_b32 m0, s13
	s_nop 0
	global_load_lds_dwordx4 v[244:245], off
	s_waitcnt vmcnt(8) lgkmcnt(0)
	s_setprio 1
	s_barrier
; #define PG8_STAGE(bufoff, gbase, voff) do { _Pragma("unroll") for (int _i = 0; _i < 2; ++_i) \
;         __builtin_amdgcn_global_load_lds((const unsigned*)((const char*)(gbase) + (voff)[_i]), (PG8_LAS unsigned*)(lds + (bufoff) + ldsw + _i * 8192), 16, 0, 0); } while (0)
; #define PG8_LDA(dst, b, h) do { _Pragma("unroll") for (int m = 0; m < 4; ++m) _Pragma("unroll") for (int k = 0; k < 2; ++k) dst[m][k] = *(const PG8_LAS bf16x8*)(lds + PG8_SA(b, h) + aoff + m * 2048 + k * 1024); } while (0)
; #define PG8_LDB(dst, b, h) do { _Pragma("unroll") for (int n = 0; n < 2; ++n) _Pragma("unroll") for (int k = 0; k < 2; ++k) dst[n][k] = *(const PG8_LAS bf16x8*)(lds + PG8_SB(b, h) + boff + n * 2048 + k * 1024); } while (0)
; #define PG8_MMA(ai, bj, At, Bt) do { __builtin_amdgcn_s_setprio(1); _Pragma("unroll") for (int m = 0; m < 4; ++m) _Pragma("unroll") for (int n = 0; n < 2; ++n) _Pragma("unroll") for (int k = 0; k < 2; ++k) \
;         acc[ai][bj][m][n] = __builtin_amdgcn_mfma_f32_16x16x32_bf16(Bt[n][k], At[m][k], acc[ai][bj][m][n], 0, 0, 0); __builtin_amdgcn_s_setprio(0); } while (0)
; #define PG8_WAIT_V(n) asm volatile("s_waitcnt vmcnt(" #n ")" ::: "memory")
; #define PG8_WAIT_L(n) asm volatile("s_waitcnt lgkmcnt(" #n ")" ::: "memory")
; #define PG8_BAR __builtin_amdgcn_s_barrier()
; #define PG8_SCHED __builtin_amdgcn_sched_barrier(0)
; template <class Epi, class Sched, bool ALIGN_EPI = false, bool SP2 = false>
; __device__ __forceinline__ void gemm_phase(PG8_LAS unsigned char* lds, const Gemm g, const Sched& S, const Epi& E) {
;     ...
;             PG8_WAIT_V(8); PG8_WAIT_L(0); PG8_BAR; PG8_MMA(0, 0, At, B0); PG8_MMA(0, 1, At, B1); PG8_BAR; PG8_SCHED;
;             PG8_LDA(At, 0, 1); PG8_STAGE(PG8_SB(0, 0), b2, voffB); PG8_STAGE(PG8_SB(0, 1), b2 + hstep, voffB); PG8_STAGE(PG8_SA(0, 0), a2, voffA);
;             PG8_WAIT_V(8); PG8_WAIT_L(0); PG8_BAR; PG8_MMA(1, 0, At, B0); PG8_MMA(1, 1, At, B1); PG8_BAR; PG8_SCHED;
;             PG8_LDB(B0, 1, 0); PG8_LDB(B1, 1, 1); PG8_SCHED; PG8_LDA(At, 1, 0); PG8_STAGE(PG8_SA(0, 1), a2 + hstep, voffA);
;             PG8_WAIT_V(8); PG8_WAIT_L(0); PG8_BAR; PG8_MMA(0, 0, At, B0); PG8_MMA(0, 1, At, B1); PG8_BAR; PG8_SCHED;
	v_mfma_f32_16x16x32_bf16 v[62:65], v[160:163], v[192:195], v[62:65]
	v_mfma_f32_16x16x32_bf16 v[58:61], v[168:171], v[192:195], v[58:61]
	v_mfma_f32_16x16x32_bf16 v[54:57], v[160:163], v[200:203], v[54:57]
	v_mfma_f32_16x16x32_bf16 v[50:53], v[168:171], v[200:203], v[50:53]
	v_mfma_f32_16x16x32_bf16 v[38:41], v[160:163], v[208:211], v[38:41]
	v_mfma_f32_16x16x32_bf16 v[34:37], v[168:171], v[208:211], v[34:37]
	v_mfma_f32_16x16x32_bf16 v[22:25], v[160:163], v[216:219], v[22:25]
	v_mfma_f32_16x16x32_bf16 v[18:21], v[168:171], v[216:219], v[18:21]
	v_mfma_f32_16x16x32_bf16 v[62:65], v[164:167], v[196:199], v[62:65]
	v_mfma_f32_16x16x32_bf16 v[58:61], v[172:175], v[196:199], v[58:61]
	v_mfma_f32_16x16x32_bf16 v[54:57], v[164:167], v[204:207], v[54:57]
	v_mfma_f32_16x16x32_bf16 v[50:53], v[172:175], v[204:207], v[50:53]
	v_mfma_f32_16x16x32_bf16 v[38:41], v[164:167], v[212:215], v[38:41]
	v_mfma_f32_16x16x32_bf16 v[34:37], v[172:175], v[212:215], v[34:37]
	v_mfma_f32_16x16x32_bf16 v[22:25], v[164:167], v[224:227], v[22:25]
	v_mfma_f32_16x16x32_bf16 v[18:21], v[172:175], v[224:227], v[18:21]
	v_mfma_f32_16x16x32_bf16 v[46:49], v[176:179], v[192:195], v[46:49]
	v_mfma_f32_16x16x32_bf16 v[42:45], v[184:187], v[192:195], v[42:45]
	v_mfma_f32_16x16x32_bf16 v[30:33], v[176:179], v[200:203], v[30:33]
	v_mfma_f32_16x16x32_bf16 v[26:29], v[184:187], v[200:203], v[26:29]
	v_mfma_f32_16x16x32_bf16 v[14:17], v[176:179], v[208:211], v[14:17]
	v_mfma_f32_16x16x32_bf16 v[10:13], v[184:187], v[208:211], v[10:13]
	v_mfma_f32_16x16x32_bf16 v[6:9], v[176:179], v[216:219], v[6:9]
	v_mfma_f32_16x16x32_bf16 v[2:5], v[184:187], v[216:219], v[2:5]
	v_mfma_f32_16x16x32_bf16 v[46:49], v[180:183], v[196:199], v[46:49]
	v_mfma_f32_16x16x32_bf16 v[42:45], v[188:191], v[196:199], v[42:45]
	v_mfma_f32_16x16x32_bf16 v[30:33], v[180:183], v[204:207], v[30:33]
	v_mfma_f32_16x16x32_bf16 v[26:29], v[188:191], v[204:207], v[26:29]
	v_mfma_f32_16x16x32_bf16 v[14:17], v[180:183], v[212:215], v[14:17]
	v_mfma_f32_16x16x32_bf16 v[10:13], v[188:191], v[212:215], v[10:13]
	v_mfma_f32_16x16x32_bf16 v[6:9], v[180:183], v[224:227], v[6:9]
	v_mfma_f32_16x16x32_bf16 v[2:5], v[188:191], v[224:227], v[2:5]
	s_barrier
	s_setprio 0
	s_add_i32 s20, 0, 0x18000
	s_add_i32 s21, 0, 0x1c000
	v_add_u32_e32 v172, s20, v158
	v_add_u32_e32 v188, s21, v158
	ds_read_b128 v[160:163], v172
	ds_read_b128 v[164:167], v172 offset:1024
	ds_read_b128 v[168:171], v172 offset:2048
	ds_read_b128 v[172:175], v172 offset:3072
	ds_read_b128 v[176:179], v188
	ds_read_b128 v[180:183], v188 offset:1024
	ds_read_b128 v[184:187], v188 offset:2048
	ds_read_b128 v[188:191], v188 offset:3072
	s_add_u32 s6, s6, 0x80000
	s_addc_u32 s7, s7, 0
	s_mov_b32 m0, s14
	v_lshl_add_u64 v[246:247], s[6:7], 0, v[150:151]
	ds_read_b128 v[192:195], v159 offset:32768
	ds_read_b128 v[196:199], v159 offset:33792
	ds_read_b128 v[200:203], v159 offset:34816
	ds_read_b128 v[204:207], v159 offset:35840
	ds_read_b128 v[208:211], v159 offset:36864
	ds_read_b128 v[212:215], v159 offset:37888
	ds_read_b128 v[216:219], v159 offset:38912
	ds_read_b128 v[224:227], v159 offset:39936
	global_load_lds_dwordx4 v[246:247], off
	s_mov_b32 m0, s15
	v_lshl_add_u64 v[246:247], s[6:7], 0, v[148:149]
	global_load_lds_dwordx4 v[246:247], off
	s_waitcnt vmcnt(8) lgkmcnt(0)
	s_setprio 1
	s_barrier
	v_mfma_f32_16x16x32_bf16 v[144:147], v[160:163], v[192:195], v[144:147]
	v_mfma_f32_16x16x32_bf16 v[122:125], v[168:171], v[192:195], v[122:125]
	v_mfma_f32_16x16x32_bf16 v[118:121], v[160:163], v[200:203], v[118:121]
	v_mfma_f32_16x16x32_bf16 v[114:117], v[168:171], v[200:203], v[114:117]
	v_mfma_f32_16x16x32_bf16 v[102:105], v[160:163], v[208:211], v[102:105]
	v_mfma_f32_16x16x32_bf16 v[98:101], v[168:171], v[208:211], v[98:101]
	v_mfma_f32_16x16x32_bf16 v[86:89], v[160:163], v[216:219], v[86:89]
	v_mfma_f32_16x16x32_bf16 v[82:85], v[168:171], v[216:219], v[82:85]
	v_mfma_f32_16x16x32_bf16 v[144:147], v[164:167], v[196:199], v[144:147]
	v_mfma_f32_16x16x32_bf16 v[122:125], v[172:175], v[196:199], v[122:125]
	v_mfma_f32_16x16x32_bf16 v[118:121], v[164:167], v[204:207], v[118:121]
	v_mfma_f32_16x16x32_bf16 v[114:117], v[172:175], v[204:207], v[114:117]
	v_mfma_f32_16x16x32_bf16 v[102:105], v[164:167], v[212:215], v[102:105]
	v_mfma_f32_16x16x32_bf16 v[98:101], v[172:175], v[212:215], v[98:101]
	v_mfma_f32_16x16x32_bf16 v[86:89], v[164:167], v[224:227], v[86:89]
	v_mfma_f32_16x16x32_bf16 v[82:85], v[172:175], v[224:227], v[82:85]
	v_mfma_f32_16x16x32_bf16 v[110:113], v[176:179], v[192:195], v[110:113]
	v_mfma_f32_16x16x32_bf16 v[106:109], v[184:187], v[192:195], v[106:109]
	v_mfma_f32_16x16x32_bf16 v[94:97], v[176:179], v[200:203], v[94:97]
	v_mfma_f32_16x16x32_bf16 v[90:93], v[184:187], v[200:203], v[90:93]
	v_mfma_f32_16x16x32_bf16 v[78:81], v[176:179], v[208:211], v[78:81]
	v_mfma_f32_16x16x32_bf16 v[74:77], v[184:187], v[208:211], v[74:77]
	v_mfma_f32_16x16x32_bf16 v[70:73], v[176:179], v[216:219], v[70:73]
	v_mfma_f32_16x16x32_bf16 v[66:69], v[184:187], v[216:219], v[66:69]
	v_mfma_f32_16x16x32_bf16 v[110:113], v[180:183], v[196:199], v[110:113]
	v_mfma_f32_16x16x32_bf16 v[106:109], v[188:191], v[196:199], v[106:109]
	v_mfma_f32_16x16x32_bf16 v[94:97], v[180:183], v[204:207], v[94:97]
	v_mfma_f32_16x16x32_bf16 v[90:93], v[188:191], v[204:207], v[90:93]
	v_mfma_f32_16x16x32_bf16 v[78:81], v[180:183], v[212:215], v[78:81]
	v_mfma_f32_16x16x32_bf16 v[74:77], v[188:191], v[212:215], v[74:77]
	v_mfma_f32_16x16x32_bf16 v[70:73], v[180:183], v[224:227], v[70:73]
	v_mfma_f32_16x16x32_bf16 v[66:69], v[188:191], v[224:227], v[66:69]
	s_barrier
; #define PG8_STAGE(bufoff, gbase, voff) do { _Pragma("unroll") for (int _i = 0; _i < 2; ++_i) \
;         __builtin_amdgcn_global_load_lds((const unsigned*)((const char*)(gbase) + (voff)[_i]), (PG8_LAS unsigned*)(lds + (bufoff) + ldsw + _i * 8192), 16, 0, 0); } while (0)
; #define PG8_LDA(dst, b, h) do { _Pragma("unroll") for (int m = 0; m < 4; ++m) _Pragma("unroll") for (int k = 0; k < 2; ++k) dst[m][k] = *(const PG8_LAS bf16x8*)(lds + PG8_SA(b, h) + aoff + m * 2048 + k * 1024); } while (0)
; #define PG8_WAIT_V(n) asm volatile("s_waitcnt vmcnt(" #n ")" ::: "memory")
; template <class Epi, class Sched, bool ALIGN_EPI = false, bool SP2 = false>
; __device__ __forceinline__ void gemm_phase(PG8_LAS unsigned char* lds, const Gemm g, const Sched& S, const Epi& E) {
;     ...
;         for (int t = 0; t < nt; t += 2) {
;             if constexpr (Epi::HAS_MID) { if (t == Epi::MID0 || t == Epi::MID1) E.mid(acc, cur, wr, wc, fr, fq, t == Epi::MID0 ? 0 : 1); }
;             const bool last = (t == nt - 2);
;             const char* a1 = cA + (size_t)(t + 1) * kstep;
;             const char* a2 = last ? nA : cA + (size_t)(t + 2) * kstep; const char* b2 = last ? nB : cB + (size_t)(t + 2) * kstep;
;             const char* a3 = a2 + kstep; const char* b3 = b2 + kstep;
;             if (last && has_next) S.a_ready(nxt);
;             if constexpr (SP2) {
;             PG8_LDB(B0, 0, 0); PG8_LDB(B1, 0, 1); PG8_SCHED; PG8_LDA(At, 0, 0); PG8_STAGE(PG8_SA(1, 1), a1 + hstep, voffA);
;             PG8_WAIT_V(8); PG8_WAIT_L(0); PG8_BAR; PG8_MMA(0, 0, At, B0); PG8_MMA(0, 1, At, B1); PG8_BAR; PG8_SCHED;
;             PG8_LDA(At, 0, 1); PG8_STAGE(PG8_SB(0, 0), b2, voffB); PG8_STAGE(PG8_SB(0, 1), b2 + hstep, voffB); PG8_STAGE(PG8_SA(0, 0), a2, voffA);
;             PG8_WAIT_V(8); PG8_WAIT_L(0); PG8_BAR; PG8_MMA(1, 0, At, B0); PG8_MMA(1, 1, At, B1); PG8_BAR; PG8_SCHED;
;             PG8_LDB(B0, 1, 0); PG8_LDB(B1, 1, 1); PG8_SCHED; PG8_LDA(At, 1, 0); PG8_STAGE(PG8_SA(0, 1), a2 + hstep, voffA);
;             PG8_WAIT_V(8); PG8_WAIT_L(0); PG8_BAR; PG8_MMA(0, 0, At, B0); PG8_MMA(0, 1, At, B1); PG8_BAR; PG8_SCHED;
;             PG8_LDA(At, 1, 1); PG8_STAGE(PG8_SB(1, 0), b3, voffB); PG8_STAGE(PG8_SB(1, 1), b3 + hstep, voffB); PG8_STAGE(PG8_SA(1, 0), a3, voffA);
;             PG8_WAIT_V(8); PG8_WAIT_L(0); PG8_BAR; PG8_MMA(1, 0, At, B0); PG8_MMA(1, 1, At, B1); PG8_BAR; PG8_SCHED;
	s_setprio 0
	s_add_i32 s6, s20, s9
	v_lshl_add_u64 v[228:229], v[228:229], 0, s[64:65]
	s_mov_b32 m0, s6
	ds_read_b128 v[192:195], v159 offset:49152
	ds_read_b128 v[196:199], v159 offset:50176
	ds_read_b128 v[200:203], v159 offset:51200
	ds_read_b128 v[204:207], v159 offset:52224
	ds_read_b128 v[208:211], v159 offset:53248
	ds_read_b128 v[212:215], v159 offset:54272
	ds_read_b128 v[216:219], v159 offset:55296
	ds_read_b128 v[224:227], v159 offset:56320
	global_load_lds_dwordx4 v[228:229], off
	s_add_i32 m0, s6, 0x2000
	s_add_u32 s4, s4, 0x80080
	v_lshl_add_u64 v[228:229], v[230:231], 0, s[64:65]
	s_addc_u32 s5, s5, 0
	s_add_i32 s6, s21, s9
	global_load_lds_dwordx4 v[228:229], off
	s_mov_b32 m0, s6
	v_lshl_add_u64 v[228:229], s[4:5], 0, v[0:1]
	global_load_lds_dwordx4 v[228:229], off
	s_add_i32 m0, s6, 0x2000
	v_lshl_add_u64 v[228:229], s[4:5], 0, v[126:127]
	global_load_lds_dwordx4 v[228:229], off
	s_mov_b32 m0, s17
	v_lshl_add_u64 v[228:229], v[232:233], 0, s[64:65]
	global_load_lds_dwordx4 v[228:229], off
	s_mov_b32 m0, s18
	v_lshl_add_u64 v[228:229], v[244:245], 0, s[64:65]
	global_load_lds_dwordx4 v[228:229], off
	s_waitcnt vmcnt(8) lgkmcnt(0)
	s_setprio 1
	s_barrier
	v_mfma_f32_16x16x32_bf16 v[62:65], v[160:163], v[192:195], v[62:65]
	v_mfma_f32_16x16x32_bf16 v[58:61], v[168:171], v[192:195], v[58:61]
	v_mfma_f32_16x16x32_bf16 v[54:57], v[160:163], v[200:203], v[54:57]
	v_mfma_f32_16x16x32_bf16 v[50:53], v[168:171], v[200:203], v[50:53]
	v_mfma_f32_16x16x32_bf16 v[38:41], v[160:163], v[208:211], v[38:41]
	v_mfma_f32_16x16x32_bf16 v[34:37], v[168:171], v[208:211], v[34:37]
	v_mfma_f32_16x16x32_bf16 v[22:25], v[160:163], v[216:219], v[22:25]
	v_mfma_f32_16x16x32_bf16 v[18:21], v[168:171], v[216:219], v[18:21]
	v_mfma_f32_16x16x32_bf16 v[62:65], v[164:167], v[196:199], v[62:65]
	v_mfma_f32_16x16x32_bf16 v[58:61], v[172:175], v[196:199], v[58:61]
	v_mfma_f32_16x16x32_bf16 v[54:57], v[164:167], v[204:207], v[54:57]
	v_mfma_f32_16x16x32_bf16 v[50:53], v[172:175], v[204:207], v[50:53]
	v_mfma_f32_16x16x32_bf16 v[38:41], v[164:167], v[212:215], v[38:41]
	v_mfma_f32_16x16x32_bf16 v[34:37], v[172:175], v[212:215], v[34:37]
	v_mfma_f32_16x16x32_bf16 v[22:25], v[164:167], v[224:227], v[22:25]
	v_mfma_f32_16x16x32_bf16 v[18:21], v[172:175], v[224:227], v[18:21]
	v_mfma_f32_16x16x32_bf16 v[46:49], v[176:179], v[192:195], v[46:49]
	v_mfma_f32_16x16x32_bf16 v[42:45], v[184:187], v[192:195], v[42:45]
	v_mfma_f32_16x16x32_bf16 v[30:33], v[176:179], v[200:203], v[30:33]
	v_mfma_f32_16x16x32_bf16 v[26:29], v[184:187], v[200:203], v[26:29]
	v_mfma_f32_16x16x32_bf16 v[14:17], v[176:179], v[208:211], v[14:17]
	v_mfma_f32_16x16x32_bf16 v[10:13], v[184:187], v[208:211], v[10:13]
	v_mfma_f32_16x16x32_bf16 v[6:9], v[176:179], v[216:219], v[6:9]
	v_mfma_f32_16x16x32_bf16 v[2:5], v[184:187], v[216:219], v[2:5]
	v_mfma_f32_16x16x32_bf16 v[46:49], v[180:183], v[196:199], v[46:49]
	v_mfma_f32_16x16x32_bf16 v[42:45], v[188:191], v[196:199], v[42:45]
	v_mfma_f32_16x16x32_bf16 v[30:33], v[180:183], v[204:207], v[30:33]
	v_mfma_f32_16x16x32_bf16 v[26:29], v[188:191], v[204:207], v[26:29]
	v_mfma_f32_16x16x32_bf16 v[14:17], v[180:183], v[212:215], v[14:17]
	v_mfma_f32_16x16x32_bf16 v[10:13], v[188:191], v[212:215], v[10:13]
	v_mfma_f32_16x16x32_bf16 v[6:9], v[180:183], v[224:227], v[6:9]
	v_mfma_f32_16x16x32_bf16 v[2:5], v[188:191], v[224:227], v[2:5]
	s_barrier
	s_setprio 0
	s_add_i32 s19, s19, 2
	s_add_u32 s0, s0, 0x100
	s_addc_u32 s1, s1, 0
	s_cmp_gt_u32 s19, 29
	s_cbranch_scc0 .LBB0_307
	s_cmpk_lt_u32 s8, 0x100
	s_cbranch_scc0 .LBB0_310
	s_barrier

; #define PG8_STAGE(bufoff, gbase, voff) do { _Pragma("unroll") for (int _i = 0; _i < 2; ++_i) \
;         __builtin_amdgcn_global_load_lds((const unsigned*)((const char*)(gbase) + (voff)[_i]), (PG8_LAS unsigned*)(lds + (bufoff) + ldsw + _i * 8192), 16, 0, 0); } while (0)
; #define PG8_LDA(dst, b, h) do { _Pragma("unroll") for (int m = 0; m < 4; ++m) _Pragma("unroll") for (int k = 0; k < 2; ++k) dst[m][k] = *(const PG8_LAS bf16x8*)(lds + PG8_SA(b, h) + aoff + m * 2048 + k * 1024); } while (0)
; #define PG8_LDB(dst, b, h) do { _Pragma("unroll") for (int n = 0; n < 2; ++n) _Pragma("unroll") for (int k = 0; k < 2; ++k) dst[n][k] = *(const PG8_LAS bf16x8*)(lds + PG8_SB(b, h) + boff + n * 2048 + k * 1024); } while (0)
; #define PG8_BAR __builtin_amdgcn_s_barrier()
; template <class Epi, class Sched, bool ALIGN_EPI = false, bool SP2 = false>
; __device__ __forceinline__ void gemm_phase(PG8_LAS unsigned char* lds, const Gemm g, const Sched& S, const Epi& E) {
;     ...
;             const bool last = (t == nt - 2);
;             const char* a1 = cA + (size_t)(t + 1) * kstep;
;             const char* a2 = last ? nA : cA + (size_t)(t + 2) * kstep; const char* b2 = last ? nB : cB + (size_t)(t + 2) * kstep;
;             const char* a3 = a2 + kstep; const char* b3 = b2 + kstep;
;             if (last && has_next) S.a_ready(nxt);
;             if constexpr (SP2) {
;             PG8_LDB(B0, 0, 0); PG8_LDB(B1, 0, 1); PG8_SCHED; PG8_LDA(At, 0, 0); PG8_STAGE(PG8_SA(1, 1), a1 + hstep, voffA);
;             PG8_WAIT_V(8); PG8_WAIT_L(0); PG8_BAR; PG8_MMA(0, 0, At, B0); PG8_MMA(0, 1, At, B1); PG8_BAR; PG8_SCHED;
;             PG8_LDA(At, 0, 1); PG8_STAGE(PG8_SB(0, 0), b2, voffB); PG8_STAGE(PG8_SB(0, 1), b2 + hstep, voffB); PG8_STAGE(PG8_SA(0, 0), a2, voffA);
;             PG8_WAIT_V(8); PG8_WAIT_L(0); PG8_BAR; PG8_MMA(1, 0, At, B0); PG8_MMA(1, 1, At, B1); PG8_BAR; PG8_SCHED;
;             PG8_LDB(B0, 1, 0); PG8_LDB(B1, 1, 1); PG8_SCHED; PG8_LDA(At, 1, 0); PG8_STAGE(PG8_SA(0, 1), a2 + hstep, voffA);
;             PG8_WAIT_V(8); PG8_WAIT_L(0); PG8_BAR; PG8_MMA(0, 0, At, B0); PG8_MMA(0, 1, At, B1); PG8_BAR; PG8_SCHED;
;             PG8_LDA(At, 1, 1); PG8_STAGE(PG8_SB(1, 0), b3, voffB); PG8_STAGE(PG8_SB(1, 1), b3 + hstep, voffB); PG8_STAGE(PG8_SA(1, 0), a3, voffA);
;             PG8_WAIT_V(8); PG8_WAIT_L(0); PG8_BAR; PG8_MMA(1, 0, At, B0); PG8_MMA(1, 1, At, B1); PG8_BAR; PG8_SCHED;
.LBB0_733:
	s_add_u32 s22, s18, s20
	s_addc_u32 s23, s19, s21
	s_add_u32 s22, s22, 0x100
	s_addc_u32 s23, s23, 0
	s_add_u32 s26, s86, s20
	s_addc_u32 s27, s87, s21
	s_add_i32 s40, 0, 0x10000
	s_cmpk_eq_i32 s20, 0xf00
	s_cselect_b32 s25, s13, s23
	s_cselect_b32 s24, s82, s22
	s_cselect_b32 s23, s9, s27
	s_cselect_b32 s22, s83, s26
	s_add_i32 s41, 0, 0x14000
	v_add_u32_e32 v160, s40, v245
	v_add_u32_e32 v176, s41, v245
	ds_read_b128 v[148:151], v160
	ds_read_b128 v[152:155], v160 offset:1024
	ds_read_b128 v[156:159], v160 offset:2048
	ds_read_b128 v[160:163], v160 offset:3072
	ds_read_b128 v[164:167], v176
	ds_read_b128 v[168:171], v176 offset:1024
	ds_read_b128 v[172:175], v176 offset:2048
	ds_read_b128 v[176:179], v176 offset:3072
	v_lshl_add_u64 v[232:233], v[228:229], 0, s[20:21]
	s_add_i32 m0, s31, 0xc000
	ds_read_b128 v[180:183], v247
	ds_read_b128 v[184:187], v247 offset:1024
	ds_read_b128 v[188:191], v247 offset:2048
	ds_read_b128 v[192:195], v247 offset:3072
	ds_read_b128 v[196:199], v247 offset:4096
	ds_read_b128 v[200:203], v247 offset:5120
	ds_read_b128 v[204:207], v247 offset:6144
	ds_read_b128 v[208:211], v247 offset:7168
	global_load_lds_dwordx4 v[232:233], off
	s_add_i32 m0, s31, 0xe000
	v_lshl_add_u64 v[232:233], v[230:231], 0, s[20:21]
	global_load_lds_dwordx4 v[232:233], off
	s_waitcnt vmcnt(8) lgkmcnt(0)
	s_setprio 1
	s_barrier
	v_mfma_f32_16x16x32_bf16 v[144:147], v[148:151], v[180:183], v[144:147]
	v_mfma_f32_16x16x32_bf16 v[122:125], v[156:159], v[180:183], v[122:125]
	v_mfma_f32_16x16x32_bf16 v[110:113], v[148:151], v[188:191], v[110:113]
	v_mfma_f32_16x16x32_bf16 v[106:109], v[156:159], v[188:191], v[106:109]
	v_mfma_f32_16x16x32_bf16 v[94:97], v[148:151], v[196:199], v[94:97]
	v_mfma_f32_16x16x32_bf16 v[90:93], v[156:159], v[196:199], v[90:93]
	v_mfma_f32_16x16x32_bf16 v[78:81], v[148:151], v[204:207], v[78:81]
	v_mfma_f32_16x16x32_bf16 v[74:77], v[156:159], v[204:207], v[74:77]
	v_mfma_f32_16x16x32_bf16 v[144:147], v[152:155], v[184:187], v[144:147]
	v_mfma_f32_16x16x32_bf16 v[122:125], v[160:163], v[184:187], v[122:125]
	v_mfma_f32_16x16x32_bf16 v[110:113], v[152:155], v[192:195], v[110:113]
	v_mfma_f32_16x16x32_bf16 v[106:109], v[160:163], v[192:195], v[106:109]
	v_mfma_f32_16x16x32_bf16 v[94:97], v[152:155], v[200:203], v[94:97]
	v_mfma_f32_16x16x32_bf16 v[90:93], v[160:163], v[200:203], v[90:93]
	v_mfma_f32_16x16x32_bf16 v[78:81], v[152:155], v[208:211], v[78:81]
	v_mfma_f32_16x16x32_bf16 v[74:77], v[160:163], v[208:211], v[74:77]
	v_mfma_f32_16x16x32_bf16 v[118:121], v[164:167], v[180:183], v[118:121]
	v_mfma_f32_16x16x32_bf16 v[114:117], v[172:175], v[180:183], v[114:117]
	v_mfma_f32_16x16x32_bf16 v[102:105], v[164:167], v[188:191], v[102:105]
	v_mfma_f32_16x16x32_bf16 v[98:101], v[172:175], v[188:191], v[98:101]
	v_mfma_f32_16x16x32_bf16 v[86:89], v[164:167], v[196:199], v[86:89]
	v_mfma_f32_16x16x32_bf16 v[82:85], v[172:175], v[196:199], v[82:85]
	v_mfma_f32_16x16x32_bf16 v[70:73], v[164:167], v[204:207], v[70:73]
	v_mfma_f32_16x16x32_bf16 v[66:69], v[172:175], v[204:207], v[66:69]
	v_mfma_f32_16x16x32_bf16 v[118:121], v[168:171], v[184:187], v[118:121]
	v_mfma_f32_16x16x32_bf16 v[114:117], v[176:179], v[184:187], v[114:117]
	v_mfma_f32_16x16x32_bf16 v[102:105], v[168:171], v[192:195], v[102:105]
	v_mfma_f32_16x16x32_bf16 v[98:101], v[176:179], v[192:195], v[98:101]
	v_mfma_f32_16x16x32_bf16 v[86:89], v[168:171], v[200:203], v[86:89]
	v_mfma_f32_16x16x32_bf16 v[82:85], v[176:179], v[200:203], v[82:85]
	v_mfma_f32_16x16x32_bf16 v[70:73], v[168:171], v[208:211], v[70:73]
	v_mfma_f32_16x16x32_bf16 v[66:69], v[176:179], v[208:211], v[66:69]
	s_barrier
	s_setprio 0
	s_add_i32 s26, s40, s30
	v_lshl_add_u64 v[232:233], s[22:23], 0, v[0:1]
	s_mov_b32 m0, s26
	ds_read_b128 v[180:183], v247 offset:16384
	ds_read_b128 v[184:187], v247 offset:17408
	ds_read_b128 v[188:191], v247 offset:18432
	ds_read_b128 v[192:195], v247 offset:19456
	ds_read_b128 v[196:199], v247 offset:20480
	ds_read_b128 v[200:203], v247 offset:21504
	ds_read_b128 v[204:207], v247 offset:22528
	ds_read_b128 v[208:211], v247 offset:23552
	global_load_lds_dwordx4 v[232:233], off
	s_add_i32 m0, s26, 0x2000
	s_add_u32 s26, s22, 0x80000
	v_lshl_add_u64 v[248:249], s[22:23], 0, v[126:127]
	s_addc_u32 s27, s23, 0
	s_add_i32 s40, s41, s30
	global_load_lds_dwordx4 v[248:249], off
	v_lshl_add_u64 v[250:251], s[26:27], 0, v[0:1]
	s_mov_b32 m0, s40
	v_lshl_add_u64 v[220:221], s[24:25], 0, v[212:213]
	global_load_lds_dwordx4 v[250:251], off
	s_add_i32 m0, s40, 0x2000
	v_lshl_add_u64 v[250:251], s[26:27], 0, v[126:127]
	global_load_lds_dwordx4 v[250:251], off
	s_mov_b32 m0, s31
	v_lshl_add_u64 v[250:251], s[24:25], 0, v[214:215]
	global_load_lds_dwordx4 v[250:251], off
	s_mov_b32 m0, s34
	s_nop 0
	global_load_lds_dwordx4 v[220:221], off
	s_waitcnt vmcnt(8) lgkmcnt(0)
	s_setprio 1
	s_barrier
; #define PG8_STAGE(bufoff, gbase, voff) do { _Pragma("unroll") for (int _i = 0; _i < 2; ++_i) \
;         __builtin_amdgcn_global_load_lds((const unsigned*)((const char*)(gbase) + (voff)[_i]), (PG8_LAS unsigned*)(lds + (bufoff) + ldsw + _i * 8192), 16, 0, 0); } while (0)
; #define PG8_LDA(dst, b, h) do { _Pragma("unroll") for (int m = 0; m < 4; ++m) _Pragma("unroll") for (int k = 0; k < 2; ++k) dst[m][k] = *(const PG8_LAS bf16x8*)(lds + PG8_SA(b, h) + aoff + m * 2048 + k * 1024); } while (0)
; #define PG8_LDB(dst, b, h) do { _Pragma("unroll") for (int n = 0; n < 2; ++n) _Pragma("unroll") for (int k = 0; k < 2; ++k) dst[n][k] = *(const PG8_LAS bf16x8*)(lds + PG8_SB(b, h) + boff + n * 2048 + k * 1024); } while (0)
; #define PG8_MMA(ai, bj, At, Bt) do { __builtin_amdgcn_s_setprio(1); _Pragma("unroll") for (int m = 0; m < 4; ++m) _Pragma("unroll") for (int n = 0; n < 2; ++n) _Pragma("unroll") for (int k = 0; k < 2; ++k) \
;         acc[ai][bj][m][n] = __builtin_amdgcn_mfma_f32_16x16x32_bf16(Bt[n][k], At[m][k], acc[ai][bj][m][n], 0, 0, 0); __builtin_amdgcn_s_setprio(0); } while (0)
; #define PG8_WAIT_V(n) asm volatile("s_waitcnt vmcnt(" #n ")" ::: "memory")
; #define PG8_WAIT_L(n) asm volatile("s_waitcnt lgkmcnt(" #n ")" ::: "memory")
; #define PG8_BAR __builtin_amdgcn_s_barrier()
; #define PG8_SCHED __builtin_amdgcn_sched_barrier(0)
; template <class Epi, class Sched, bool ALIGN_EPI = false, bool SP2 = false>
; __device__ __forceinline__ void gemm_phase(PG8_LAS unsigned char* lds, const Gemm g, const Sched& S, const Epi& E) {
;     ...
;             PG8_WAIT_V(8); PG8_WAIT_L(0); PG8_BAR; PG8_MMA(0, 0, At, B0); PG8_MMA(0, 1, At, B1); PG8_BAR; PG8_SCHED;
;             PG8_LDA(At, 0, 1); PG8_STAGE(PG8_SB(0, 0), b2, voffB); PG8_STAGE(PG8_SB(0, 1), b2 + hstep, voffB); PG8_STAGE(PG8_SA(0, 0), a2, voffA);
;             PG8_WAIT_V(8); PG8_WAIT_L(0); PG8_BAR; PG8_MMA(1, 0, At, B0); PG8_MMA(1, 1, At, B1); PG8_BAR; PG8_SCHED;
;             PG8_LDB(B0, 1, 0); PG8_LDB(B1, 1, 1); PG8_SCHED; PG8_LDA(At, 1, 0); PG8_STAGE(PG8_SA(0, 1), a2 + hstep, voffA);
;             PG8_WAIT_V(8); PG8_WAIT_L(0); PG8_BAR; PG8_MMA(0, 0, At, B0); PG8_MMA(0, 1, At, B1); PG8_BAR; PG8_SCHED;
	v_mfma_f32_16x16x32_bf16 v[62:65], v[148:151], v[180:183], v[62:65]
	v_mfma_f32_16x16x32_bf16 v[58:61], v[156:159], v[180:183], v[58:61]
	v_mfma_f32_16x16x32_bf16 v[46:49], v[148:151], v[188:191], v[46:49]
	v_mfma_f32_16x16x32_bf16 v[42:45], v[156:159], v[188:191], v[42:45]
	v_mfma_f32_16x16x32_bf16 v[30:33], v[148:151], v[196:199], v[30:33]
	v_mfma_f32_16x16x32_bf16 v[26:29], v[156:159], v[196:199], v[26:29]
	v_mfma_f32_16x16x32_bf16 v[14:17], v[148:151], v[204:207], v[14:17]
	v_mfma_f32_16x16x32_bf16 v[10:13], v[156:159], v[204:207], v[10:13]
	v_mfma_f32_16x16x32_bf16 v[62:65], v[152:155], v[184:187], v[62:65]
	v_mfma_f32_16x16x32_bf16 v[58:61], v[160:163], v[184:187], v[58:61]
	v_mfma_f32_16x16x32_bf16 v[46:49], v[152:155], v[192:195], v[46:49]
	v_mfma_f32_16x16x32_bf16 v[42:45], v[160:163], v[192:195], v[42:45]
	v_mfma_f32_16x16x32_bf16 v[30:33], v[152:155], v[200:203], v[30:33]
	v_mfma_f32_16x16x32_bf16 v[26:29], v[160:163], v[200:203], v[26:29]
	v_mfma_f32_16x16x32_bf16 v[14:17], v[152:155], v[208:211], v[14:17]
	v_mfma_f32_16x16x32_bf16 v[10:13], v[160:163], v[208:211], v[10:13]
	v_mfma_f32_16x16x32_bf16 v[54:57], v[164:167], v[180:183], v[54:57]
	v_mfma_f32_16x16x32_bf16 v[50:53], v[172:175], v[180:183], v[50:53]
	v_mfma_f32_16x16x32_bf16 v[38:41], v[164:167], v[188:191], v[38:41]
	v_mfma_f32_16x16x32_bf16 v[34:37], v[172:175], v[188:191], v[34:37]
	v_mfma_f32_16x16x32_bf16 v[22:25], v[164:167], v[196:199], v[22:25]
	v_mfma_f32_16x16x32_bf16 v[18:21], v[172:175], v[196:199], v[18:21]
	v_mfma_f32_16x16x32_bf16 v[6:9], v[164:167], v[204:207], v[6:9]
	v_mfma_f32_16x16x32_bf16 v[2:5], v[172:175], v[204:207], v[2:5]
	v_mfma_f32_16x16x32_bf16 v[54:57], v[168:171], v[184:187], v[54:57]
	v_mfma_f32_16x16x32_bf16 v[50:53], v[176:179], v[184:187], v[50:53]
	v_mfma_f32_16x16x32_bf16 v[38:41], v[168:171], v[192:195], v[38:41]
	v_mfma_f32_16x16x32_bf16 v[34:37], v[176:179], v[192:195], v[34:37]
	v_mfma_f32_16x16x32_bf16 v[22:25], v[168:171], v[200:203], v[22:25]
	v_mfma_f32_16x16x32_bf16 v[18:21], v[176:179], v[200:203], v[18:21]
	v_mfma_f32_16x16x32_bf16 v[6:9], v[168:171], v[208:211], v[6:9]
	v_mfma_f32_16x16x32_bf16 v[2:5], v[176:179], v[208:211], v[2:5]
	s_barrier
	s_setprio 0
	s_add_i32 s26, 0, 0x18000
	s_add_i32 s27, 0, 0x1c000
	v_add_u32_e32 v160, s26, v245
	v_add_u32_e32 v176, s27, v245
	ds_read_b128 v[148:151], v160
	ds_read_b128 v[152:155], v160 offset:1024
	ds_read_b128 v[156:159], v160 offset:2048
	ds_read_b128 v[160:163], v160 offset:3072
	ds_read_b128 v[164:167], v176
	ds_read_b128 v[168:171], v176 offset:1024
	ds_read_b128 v[172:175], v176 offset:2048
	ds_read_b128 v[176:179], v176 offset:3072
	s_add_u32 s24, s24, 0x80000
	s_addc_u32 s25, s25, 0
	s_mov_b32 m0, s35
	v_lshl_add_u64 v[222:223], s[24:25], 0, v[214:215]
	ds_read_b128 v[180:183], v247 offset:32768
	ds_read_b128 v[184:187], v247 offset:33792
	ds_read_b128 v[188:191], v247 offset:34816
	ds_read_b128 v[192:195], v247 offset:35840
	ds_read_b128 v[196:199], v247 offset:36864
	ds_read_b128 v[200:203], v247 offset:37888
	ds_read_b128 v[204:207], v247 offset:38912
	ds_read_b128 v[208:211], v247 offset:39936
	global_load_lds_dwordx4 v[222:223], off
	s_mov_b32 m0, s36
	v_lshl_add_u64 v[222:223], s[24:25], 0, v[212:213]
	global_load_lds_dwordx4 v[222:223], off
	s_waitcnt vmcnt(8) lgkmcnt(0)
	s_setprio 1
	s_barrier
	v_mfma_f32_16x16x32_bf16 v[144:147], v[148:151], v[180:183], v[144:147]
	v_mfma_f32_16x16x32_bf16 v[122:125], v[156:159], v[180:183], v[122:125]
	v_mfma_f32_16x16x32_bf16 v[110:113], v[148:151], v[188:191], v[110:113]
	v_mfma_f32_16x16x32_bf16 v[106:109], v[156:159], v[188:191], v[106:109]
	v_mfma_f32_16x16x32_bf16 v[94:97], v[148:151], v[196:199], v[94:97]
	v_mfma_f32_16x16x32_bf16 v[90:93], v[156:159], v[196:199], v[90:93]
	v_mfma_f32_16x16x32_bf16 v[78:81], v[148:151], v[204:207], v[78:81]
	v_mfma_f32_16x16x32_bf16 v[74:77], v[156:159], v[204:207], v[74:77]
	v_mfma_f32_16x16x32_bf16 v[144:147], v[152:155], v[184:187], v[144:147]
	v_mfma_f32_16x16x32_bf16 v[122:125], v[160:163], v[184:187], v[122:125]
	v_mfma_f32_16x16x32_bf16 v[110:113], v[152:155], v[192:195], v[110:113]
	v_mfma_f32_16x16x32_bf16 v[106:109], v[160:163], v[192:195], v[106:109]
	v_mfma_f32_16x16x32_bf16 v[94:97], v[152:155], v[200:203], v[94:97]
	v_mfma_f32_16x16x32_bf16 v[90:93], v[160:163], v[200:203], v[90:93]
	v_mfma_f32_16x16x32_bf16 v[78:81], v[152:155], v[208:211], v[78:81]
	v_mfma_f32_16x16x32_bf16 v[74:77], v[160:163], v[208:211], v[74:77]
	v_mfma_f32_16x16x32_bf16 v[118:121], v[164:167], v[180:183], v[118:121]
	v_mfma_f32_16x16x32_bf16 v[114:117], v[172:175], v[180:183], v[114:117]
	v_mfma_f32_16x16x32_bf16 v[102:105], v[164:167], v[188:191], v[102:105]
	v_mfma_f32_16x16x32_bf16 v[98:101], v[172:175], v[188:191], v[98:101]
	v_mfma_f32_16x16x32_bf16 v[86:89], v[164:167], v[196:199], v[86:89]
	v_mfma_f32_16x16x32_bf16 v[82:85], v[172:175], v[196:199], v[82:85]
	v_mfma_f32_16x16x32_bf16 v[70:73], v[164:167], v[204:207], v[70:73]
	v_mfma_f32_16x16x32_bf16 v[66:69], v[172:175], v[204:207], v[66:69]
	v_mfma_f32_16x16x32_bf16 v[118:121], v[168:171], v[184:187], v[118:121]
	v_mfma_f32_16x16x32_bf16 v[114:117], v[176:179], v[184:187], v[114:117]
	v_mfma_f32_16x16x32_bf16 v[102:105], v[168:171], v[192:195], v[102:105]
	v_mfma_f32_16x16x32_bf16 v[98:101], v[176:179], v[192:195], v[98:101]
	v_mfma_f32_16x16x32_bf16 v[86:89], v[168:171], v[200:203], v[86:89]
	v_mfma_f32_16x16x32_bf16 v[82:85], v[176:179], v[200:203], v[82:85]
	v_mfma_f32_16x16x32_bf16 v[70:73], v[168:171], v[208:211], v[70:73]
	v_mfma_f32_16x16x32_bf16 v[66:69], v[176:179], v[208:211], v[66:69]
	s_barrier
; #define PG8_STAGE(bufoff, gbase, voff) do { _Pragma("unroll") for (int _i = 0; _i < 2; ++_i) \
;         __builtin_amdgcn_global_load_lds((const unsigned*)((const char*)(gbase) + (voff)[_i]), (PG8_LAS unsigned*)(lds + (bufoff) + ldsw + _i * 8192), 16, 0, 0); } while (0)
; #define PG8_LDA(dst, b, h) do { _Pragma("unroll") for (int m = 0; m < 4; ++m) _Pragma("unroll") for (int k = 0; k < 2; ++k) dst[m][k] = *(const PG8_LAS bf16x8*)(lds + PG8_SA(b, h) + aoff + m * 2048 + k * 1024); } while (0)
; #define PG8_WAIT_V(n) asm volatile("s_waitcnt vmcnt(" #n ")" ::: "memory")
; template <class Epi, class Sched, bool ALIGN_EPI = false, bool SP2 = false>
; __device__ __forceinline__ void gemm_phase(PG8_LAS unsigned char* lds, const Gemm g, const Sched& S, const Epi& E) {
;     ...
;         for (int t = 0; t < nt; t += 2) {
;             if constexpr (Epi::HAS_MID) { if (t == Epi::MID0 || t == Epi::MID1) E.mid(acc, cur, wr, wc, fr, fq, t == Epi::MID0 ? 0 : 1); }
;             const bool last = (t == nt - 2);
;             const char* a1 = cA + (size_t)(t + 1) * kstep;
;             const char* a2 = last ? nA : cA + (size_t)(t + 2) * kstep; const char* b2 = last ? nB : cB + (size_t)(t + 2) * kstep;
;             const char* a3 = a2 + kstep; const char* b3 = b2 + kstep;
;             if (last && has_next) S.a_ready(nxt);
;             if constexpr (SP2) {
;             PG8_LDB(B0, 0, 0); PG8_LDB(B1, 0, 1); PG8_SCHED; PG8_LDA(At, 0, 0); PG8_STAGE(PG8_SA(1, 1), a1 + hstep, voffA);
;             PG8_WAIT_V(8); PG8_WAIT_L(0); PG8_BAR; PG8_MMA(0, 0, At, B0); PG8_MMA(0, 1, At, B1); PG8_BAR; PG8_SCHED;
;             PG8_LDA(At, 0, 1); PG8_STAGE(PG8_SB(0, 0), b2, voffB); PG8_STAGE(PG8_SB(0, 1), b2 + hstep, voffB); PG8_STAGE(PG8_SA(0, 0), a2, voffA);
;             PG8_WAIT_V(8); PG8_WAIT_L(0); PG8_BAR; PG8_MMA(1, 0, At, B0); PG8_MMA(1, 1, At, B1); PG8_BAR; PG8_SCHED;
;             PG8_LDB(B0, 1, 0); PG8_LDB(B1, 1, 1); PG8_SCHED; PG8_LDA(At, 1, 0); PG8_STAGE(PG8_SA(0, 1), a2 + hstep, voffA);
;             PG8_WAIT_V(8); PG8_WAIT_L(0); PG8_BAR; PG8_MMA(0, 0, At, B0); PG8_MMA(0, 1, At, B1); PG8_BAR; PG8_SCHED;
;             PG8_LDA(At, 1, 1); PG8_STAGE(PG8_SB(1, 0), b3, voffB); PG8_STAGE(PG8_SB(1, 1), b3 + hstep, voffB); PG8_STAGE(PG8_SA(1, 0), a3, voffA);
;             PG8_WAIT_V(8); PG8_WAIT_L(0); PG8_BAR; PG8_MMA(1, 0, At, B0); PG8_MMA(1, 1, At, B1); PG8_BAR; PG8_SCHED;
	s_setprio 0
	s_add_i32 s24, s26, s30
	v_lshl_add_u64 v[222:223], v[232:233], 0, s[64:65]
	s_mov_b32 m0, s24
	ds_read_b128 v[180:183], v247 offset:49152
	ds_read_b128 v[184:187], v247 offset:50176
	ds_read_b128 v[188:191], v247 offset:51200
	ds_read_b128 v[192:195], v247 offset:52224
	ds_read_b128 v[196:199], v247 offset:53248
	ds_read_b128 v[200:203], v247 offset:54272
	ds_read_b128 v[204:207], v247 offset:55296
	ds_read_b128 v[208:211], v247 offset:56320
	global_load_lds_dwordx4 v[222:223], off
	s_add_i32 m0, s24, 0x2000
	s_add_u32 s22, s22, 0x80080
	v_lshl_add_u64 v[222:223], v[248:249], 0, s[64:65]
	s_addc_u32 s23, s23, 0
	s_add_i32 s24, s27, s30
	global_load_lds_dwordx4 v[222:223], off
	v_lshl_add_u64 v[222:223], s[22:23], 0, v[0:1]
	s_mov_b32 m0, s24
	v_lshl_add_u64 v[220:221], v[220:221], 0, s[64:65]
	global_load_lds_dwordx4 v[222:223], off
	s_add_i32 m0, s24, 0x2000
	v_lshl_add_u64 v[222:223], s[22:23], 0, v[126:127]
	global_load_lds_dwordx4 v[222:223], off
	s_mov_b32 m0, s37
	v_lshl_add_u64 v[222:223], v[250:251], 0, s[64:65]
	global_load_lds_dwordx4 v[222:223], off
	s_mov_b32 m0, s84
	s_nop 0
	global_load_lds_dwordx4 v[220:221], off
	s_waitcnt vmcnt(8) lgkmcnt(0)
	s_setprio 1
	s_barrier
	v_mfma_f32_16x16x32_bf16 v[62:65], v[148:151], v[180:183], v[62:65]
	v_mfma_f32_16x16x32_bf16 v[58:61], v[156:159], v[180:183], v[58:61]
	v_mfma_f32_16x16x32_bf16 v[46:49], v[148:151], v[188:191], v[46:49]
	v_mfma_f32_16x16x32_bf16 v[42:45], v[156:159], v[188:191], v[42:45]
	v_mfma_f32_16x16x32_bf16 v[30:33], v[148:151], v[196:199], v[30:33]
	v_mfma_f32_16x16x32_bf16 v[26:29], v[156:159], v[196:199], v[26:29]
	v_mfma_f32_16x16x32_bf16 v[14:17], v[148:151], v[204:207], v[14:17]
	v_mfma_f32_16x16x32_bf16 v[10:13], v[156:159], v[204:207], v[10:13]
	v_mfma_f32_16x16x32_bf16 v[62:65], v[152:155], v[184:187], v[62:65]
	v_mfma_f32_16x16x32_bf16 v[58:61], v[160:163], v[184:187], v[58:61]
	v_mfma_f32_16x16x32_bf16 v[46:49], v[152:155], v[192:195], v[46:49]
	v_mfma_f32_16x16x32_bf16 v[42:45], v[160:163], v[192:195], v[42:45]
	v_mfma_f32_16x16x32_bf16 v[30:33], v[152:155], v[200:203], v[30:33]
	v_mfma_f32_16x16x32_bf16 v[26:29], v[160:163], v[200:203], v[26:29]
	v_mfma_f32_16x16x32_bf16 v[14:17], v[152:155], v[208:211], v[14:17]
	v_mfma_f32_16x16x32_bf16 v[10:13], v[160:163], v[208:211], v[10:13]
	v_mfma_f32_16x16x32_bf16 v[54:57], v[164:167], v[180:183], v[54:57]
	v_mfma_f32_16x16x32_bf16 v[50:53], v[172:175], v[180:183], v[50:53]
	v_mfma_f32_16x16x32_bf16 v[38:41], v[164:167], v[188:191], v[38:41]
	v_mfma_f32_16x16x32_bf16 v[34:37], v[172:175], v[188:191], v[34:37]
	v_mfma_f32_16x16x32_bf16 v[22:25], v[164:167], v[196:199], v[22:25]
	v_mfma_f32_16x16x32_bf16 v[18:21], v[172:175], v[196:199], v[18:21]
	v_mfma_f32_16x16x32_bf16 v[6:9], v[164:167], v[204:207], v[6:9]
	v_mfma_f32_16x16x32_bf16 v[2:5], v[172:175], v[204:207], v[2:5]
	v_mfma_f32_16x16x32_bf16 v[54:57], v[168:171], v[184:187], v[54:57]
	v_mfma_f32_16x16x32_bf16 v[50:53], v[176:179], v[184:187], v[50:53]
	v_mfma_f32_16x16x32_bf16 v[38:41], v[168:171], v[192:195], v[38:41]
	v_mfma_f32_16x16x32_bf16 v[34:37], v[176:179], v[192:195], v[34:37]
	v_mfma_f32_16x16x32_bf16 v[22:25], v[168:171], v[200:203], v[22:25]
	v_mfma_f32_16x16x32_bf16 v[18:21], v[176:179], v[200:203], v[18:21]
	v_mfma_f32_16x16x32_bf16 v[6:9], v[168:171], v[208:211], v[6:9]
	v_mfma_f32_16x16x32_bf16 v[2:5], v[176:179], v[208:211], v[2:5]
	s_barrier
	s_setprio 0
	s_add_i32 s22, s76, 2
	s_add_u32 s20, s20, 0x100
	s_addc_u32 s21, s21, 0
	s_cmp_gt_u32 s76, 29
	s_mov_b32 s76, s22
	s_cbranch_scc1 .LBB0_742

; #define PG8_STAGE(bufoff, gbase, voff) do { _Pragma("unroll") for (int _i = 0; _i < 2; ++_i) \
;         __builtin_amdgcn_global_load_lds((const unsigned*)((const char*)(gbase) + (voff)[_i]), (PG8_LAS unsigned*)(lds + (bufoff) + ldsw + _i * 8192), 16, 0, 0); } while (0)
; #define PG8_LDA(dst, b, h) do { _Pragma("unroll") for (int m = 0; m < 4; ++m) _Pragma("unroll") for (int k = 0; k < 2; ++k) dst[m][k] = *(const PG8_LAS bf16x8*)(lds + PG8_SA(b, h) + aoff + m * 2048 + k * 1024); } while (0)
; #define PG8_LDB(dst, b, h) do { _Pragma("unroll") for (int n = 0; n < 2; ++n) _Pragma("unroll") for (int k = 0; k < 2; ++k) dst[n][k] = *(const PG8_LAS bf16x8*)(lds + PG8_SB(b, h) + boff + n * 2048 + k * 1024); } while (0)
; #define PG8_BAR __builtin_amdgcn_s_barrier()
; template <class Epi, class Sched, bool ALIGN_EPI = false, bool SP2 = false>
; __device__ __forceinline__ void gemm_phase(PG8_LAS unsigned char* lds, const Gemm g, const Sched& S, const Epi& E) {
;     ...
;             const bool last = (t == nt - 2);
;             const char* a1 = cA + (size_t)(t + 1) * kstep;
;             const char* a2 = last ? nA : cA + (size_t)(t + 2) * kstep; const char* b2 = last ? nB : cB + (size_t)(t + 2) * kstep;
;             const char* a3 = a2 + kstep; const char* b3 = b2 + kstep;
;             if (last && has_next) S.a_ready(nxt);
;             if constexpr (SP2) {
;             PG8_LDB(B0, 0, 0); PG8_LDB(B1, 0, 1); PG8_SCHED; PG8_LDA(At, 0, 0); PG8_STAGE(PG8_SA(1, 1), a1 + hstep, voffA);
;             PG8_WAIT_V(8); PG8_WAIT_L(0); PG8_BAR; PG8_MMA(0, 0, At, B0); PG8_MMA(0, 1, At, B1); PG8_BAR; PG8_SCHED;
;             PG8_LDA(At, 0, 1); PG8_STAGE(PG8_SB(0, 0), b2, voffB); PG8_STAGE(PG8_SB(0, 1), b2 + hstep, voffB); PG8_STAGE(PG8_SA(0, 0), a2, voffA);
;             PG8_WAIT_V(8); PG8_WAIT_L(0); PG8_BAR; PG8_MMA(1, 0, At, B0); PG8_MMA(1, 1, At, B1); PG8_BAR; PG8_SCHED;
;             PG8_LDB(B0, 1, 0); PG8_LDB(B1, 1, 1); PG8_SCHED; PG8_LDA(At, 1, 0); PG8_STAGE(PG8_SA(0, 1), a2 + hstep, voffA);
;             PG8_WAIT_V(8); PG8_WAIT_L(0); PG8_BAR; PG8_MMA(0, 0, At, B0); PG8_MMA(0, 1, At, B1); PG8_BAR; PG8_SCHED;
;             PG8_LDA(At, 1, 1); PG8_STAGE(PG8_SB(1, 0), b3, voffB); PG8_STAGE(PG8_SB(1, 1), b3 + hstep, voffB); PG8_STAGE(PG8_SA(1, 0), a3, voffA);
;             PG8_WAIT_V(8); PG8_WAIT_L(0); PG8_BAR; PG8_MMA(1, 0, At, B0); PG8_MMA(1, 1, At, B1); PG8_BAR; PG8_SCHED;
.LBB0_808:
	s_add_u32 s28, s8, 0xfff80080
	s_addc_u32 s29, s9, -1
	s_add_i32 s48, 0, 0x10000
	s_cmp_eq_u32 s87, 28
	s_cselect_b32 s31, s23, s29
	s_cselect_b32 s30, s67, s28
	v_add_u32_e32 v160, s48, v163
	s_cselect_b32 s29, s21, s86
	s_cselect_b32 s28, s81, s83
	s_add_i32 s91, 0, 0x14000
	ds_read_b128 v[152:155], v160
	ds_read_b128 v[156:159], v160 offset:1024
	ds_read_b128 v[166:169], v160 offset:2048
	ds_read_b128 v[170:173], v160 offset:3072
	v_add_u32_e32 v160, s91, v163
	ds_read_b128 v[174:177], v160
	ds_read_b128 v[178:181], v160 offset:1024
	ds_read_b128 v[182:185], v160 offset:2048
	ds_read_b128 v[186:189], v160 offset:3072
	v_lshl_add_u64 v[160:161], s[8:9], 0, v[148:149]
	s_add_i32 m0, s13, 0xc000
	ds_read_b128 v[190:193], v165
	ds_read_b128 v[194:197], v165 offset:1024
	ds_read_b128 v[198:201], v165 offset:2048
	ds_read_b128 v[202:205], v165 offset:3072
	ds_read_b128 v[206:209], v165 offset:4096
	ds_read_b128 v[210:213], v165 offset:5120
	ds_read_b128 v[214:217], v165 offset:6144
	ds_read_b128 v[224:227], v165 offset:7168
	global_load_lds_dwordx4 v[160:161], off
	s_add_i32 m0, s13, 0xe000
	v_lshl_add_u64 v[160:161], s[8:9], 0, v[150:151]
	global_load_lds_dwordx4 v[160:161], off
	s_waitcnt vmcnt(8) lgkmcnt(0)
	s_setprio 1
	s_barrier
	v_mfma_f32_16x16x32_bf16 v[144:147], v[152:155], v[190:193], v[144:147]
	v_mfma_f32_16x16x32_bf16 v[122:125], v[166:169], v[190:193], v[122:125]
	v_mfma_f32_16x16x32_bf16 v[110:113], v[152:155], v[198:201], v[110:113]
	v_mfma_f32_16x16x32_bf16 v[106:109], v[166:169], v[198:201], v[106:109]
	v_mfma_f32_16x16x32_bf16 v[94:97], v[152:155], v[206:209], v[94:97]
	v_mfma_f32_16x16x32_bf16 v[90:93], v[166:169], v[206:209], v[90:93]
	v_mfma_f32_16x16x32_bf16 v[78:81], v[152:155], v[214:217], v[78:81]
	v_mfma_f32_16x16x32_bf16 v[74:77], v[166:169], v[214:217], v[74:77]
	v_mfma_f32_16x16x32_bf16 v[144:147], v[156:159], v[194:197], v[144:147]
	v_mfma_f32_16x16x32_bf16 v[122:125], v[170:173], v[194:197], v[122:125]
	v_mfma_f32_16x16x32_bf16 v[110:113], v[156:159], v[202:205], v[110:113]
	v_mfma_f32_16x16x32_bf16 v[106:109], v[170:173], v[202:205], v[106:109]
	v_mfma_f32_16x16x32_bf16 v[94:97], v[156:159], v[210:213], v[94:97]
	v_mfma_f32_16x16x32_bf16 v[90:93], v[170:173], v[210:213], v[90:93]
	v_mfma_f32_16x16x32_bf16 v[78:81], v[156:159], v[224:227], v[78:81]
	v_mfma_f32_16x16x32_bf16 v[74:77], v[170:173], v[224:227], v[74:77]
	v_mfma_f32_16x16x32_bf16 v[118:121], v[174:177], v[190:193], v[118:121]
	v_mfma_f32_16x16x32_bf16 v[114:117], v[182:185], v[190:193], v[114:117]
	v_mfma_f32_16x16x32_bf16 v[102:105], v[174:177], v[198:201], v[102:105]
	v_mfma_f32_16x16x32_bf16 v[98:101], v[182:185], v[198:201], v[98:101]
	v_mfma_f32_16x16x32_bf16 v[86:89], v[174:177], v[206:209], v[86:89]
	v_mfma_f32_16x16x32_bf16 v[82:85], v[182:185], v[206:209], v[82:85]
	v_mfma_f32_16x16x32_bf16 v[70:73], v[174:177], v[214:217], v[70:73]
	v_mfma_f32_16x16x32_bf16 v[66:69], v[182:185], v[214:217], v[66:69]
	v_mfma_f32_16x16x32_bf16 v[118:121], v[178:181], v[194:197], v[118:121]
	v_mfma_f32_16x16x32_bf16 v[114:117], v[186:189], v[194:197], v[114:117]
	v_mfma_f32_16x16x32_bf16 v[102:105], v[178:181], v[202:205], v[102:105]
	v_mfma_f32_16x16x32_bf16 v[98:101], v[186:189], v[202:205], v[98:101]
	v_mfma_f32_16x16x32_bf16 v[86:89], v[178:181], v[210:213], v[86:89]
	v_mfma_f32_16x16x32_bf16 v[82:85], v[186:189], v[210:213], v[82:85]
	v_mfma_f32_16x16x32_bf16 v[70:73], v[178:181], v[224:227], v[70:73]
	v_mfma_f32_16x16x32_bf16 v[66:69], v[186:189], v[224:227], v[66:69]
	s_barrier
	s_setprio 0
	s_add_i32 s48, s48, s12
	v_lshl_add_u64 v[160:161], s[28:29], 0, v[0:1]
	s_mov_b32 m0, s48
	ds_read_b128 v[190:193], v165 offset:16384
	ds_read_b128 v[194:197], v165 offset:17408
	ds_read_b128 v[198:201], v165 offset:18432
	ds_read_b128 v[202:205], v165 offset:19456
	ds_read_b128 v[206:209], v165 offset:20480
	ds_read_b128 v[210:213], v165 offset:21504
	ds_read_b128 v[214:217], v165 offset:22528
	ds_read_b128 v[224:227], v165 offset:23552
	global_load_lds_dwordx4 v[160:161], off
	s_add_i32 m0, s48, 0x2000
	s_add_u32 vcc_lo, s28, 0x80000
	v_lshl_add_u64 v[218:219], s[28:29], 0, v[126:127]
	s_addc_u32 vcc_hi, s29, 0
	s_add_i32 s48, s91, s12
	global_load_lds_dwordx4 v[218:219], off
	v_lshl_add_u64 v[220:221], vcc, 0, v[0:1]
	s_mov_b32 m0, s48
	v_lshl_add_u64 v[222:223], s[30:31], 0, v[126:127]
	global_load_lds_dwordx4 v[220:221], off
	s_add_i32 m0, s48, 0x2000
	v_lshl_add_u64 v[220:221], vcc, 0, v[126:127]
	global_load_lds_dwordx4 v[220:221], off
	s_mov_b32 m0, s13
	v_lshl_add_u64 v[220:221], s[30:31], 0, v[0:1]
	global_load_lds_dwordx4 v[220:221], off
	s_mov_b32 m0, s34
	s_nop 0
	global_load_lds_dwordx4 v[222:223], off
	s_waitcnt vmcnt(8) lgkmcnt(0)
	s_setprio 1
	s_barrier
; #define PG8_STAGE(bufoff, gbase, voff) do { _Pragma("unroll") for (int _i = 0; _i < 2; ++_i) \
;         __builtin_amdgcn_global_load_lds((const unsigned*)((const char*)(gbase) + (voff)[_i]), (PG8_LAS unsigned*)(lds + (bufoff) + ldsw + _i * 8192), 16, 0, 0); } while (0)
; #define PG8_LDA(dst, b, h) do { _Pragma("unroll") for (int m = 0; m < 4; ++m) _Pragma("unroll") for (int k = 0; k < 2; ++k) dst[m][k] = *(const PG8_LAS bf16x8*)(lds + PG8_SA(b, h) + aoff + m * 2048 + k * 1024); } while (0)
; #define PG8_LDB(dst, b, h) do { _Pragma("unroll") for (int n = 0; n < 2; ++n) _Pragma("unroll") for (int k = 0; k < 2; ++k) dst[n][k] = *(const PG8_LAS bf16x8*)(lds + PG8_SB(b, h) + boff + n * 2048 + k * 1024); } while (0)
; #define PG8_MMA(ai, bj, At, Bt) do { __builtin_amdgcn_s_setprio(1); _Pragma("unroll") for (int m = 0; m < 4; ++m) _Pragma("unroll") for (int n = 0; n < 2; ++n) _Pragma("unroll") for (int k = 0; k < 2; ++k) \
;         acc[ai][bj][m][n] = __builtin_amdgcn_mfma_f32_16x16x32_bf16(Bt[n][k], At[m][k], acc[ai][bj][m][n], 0, 0, 0); __builtin_amdgcn_s_setprio(0); } while (0)
; #define PG8_WAIT_V(n) asm volatile("s_waitcnt vmcnt(" #n ")" ::: "memory")
; #define PG8_WAIT_L(n) asm volatile("s_waitcnt lgkmcnt(" #n ")" ::: "memory")
; #define PG8_BAR __builtin_amdgcn_s_barrier()
; #define PG8_SCHED __builtin_amdgcn_sched_barrier(0)
; template <class Epi, class Sched, bool ALIGN_EPI = false, bool SP2 = false>
; __device__ __forceinline__ void gemm_phase(PG8_LAS unsigned char* lds, const Gemm g, const Sched& S, const Epi& E) {
;     ...
;             PG8_WAIT_V(8); PG8_WAIT_L(0); PG8_BAR; PG8_MMA(0, 0, At, B0); PG8_MMA(0, 1, At, B1); PG8_BAR; PG8_SCHED;
;             PG8_LDA(At, 0, 1); PG8_STAGE(PG8_SB(0, 0), b2, voffB); PG8_STAGE(PG8_SB(0, 1), b2 + hstep, voffB); PG8_STAGE(PG8_SA(0, 0), a2, voffA);
;             PG8_WAIT_V(8); PG8_WAIT_L(0); PG8_BAR; PG8_MMA(1, 0, At, B0); PG8_MMA(1, 1, At, B1); PG8_BAR; PG8_SCHED;
;             PG8_LDB(B0, 1, 0); PG8_LDB(B1, 1, 1); PG8_SCHED; PG8_LDA(At, 1, 0); PG8_STAGE(PG8_SA(0, 1), a2 + hstep, voffA);
;             PG8_WAIT_V(8); PG8_WAIT_L(0); PG8_BAR; PG8_MMA(0, 0, At, B0); PG8_MMA(0, 1, At, B1); PG8_BAR; PG8_SCHED;
	v_mfma_f32_16x16x32_bf16 v[62:65], v[152:155], v[190:193], v[62:65]
	v_mfma_f32_16x16x32_bf16 v[58:61], v[166:169], v[190:193], v[58:61]
	v_mfma_f32_16x16x32_bf16 v[46:49], v[152:155], v[198:201], v[46:49]
	v_mfma_f32_16x16x32_bf16 v[42:45], v[166:169], v[198:201], v[42:45]
	v_mfma_f32_16x16x32_bf16 v[30:33], v[152:155], v[206:209], v[30:33]
	v_mfma_f32_16x16x32_bf16 v[26:29], v[166:169], v[206:209], v[26:29]
	v_mfma_f32_16x16x32_bf16 v[14:17], v[152:155], v[214:217], v[14:17]
	v_mfma_f32_16x16x32_bf16 v[10:13], v[166:169], v[214:217], v[10:13]
	v_mfma_f32_16x16x32_bf16 v[62:65], v[156:159], v[194:197], v[62:65]
	v_mfma_f32_16x16x32_bf16 v[58:61], v[170:173], v[194:197], v[58:61]
	v_mfma_f32_16x16x32_bf16 v[46:49], v[156:159], v[202:205], v[46:49]
	v_mfma_f32_16x16x32_bf16 v[42:45], v[170:173], v[202:205], v[42:45]
	v_mfma_f32_16x16x32_bf16 v[30:33], v[156:159], v[210:213], v[30:33]
	v_mfma_f32_16x16x32_bf16 v[26:29], v[170:173], v[210:213], v[26:29]
	v_mfma_f32_16x16x32_bf16 v[14:17], v[156:159], v[224:227], v[14:17]
	v_mfma_f32_16x16x32_bf16 v[10:13], v[170:173], v[224:227], v[10:13]
	v_mfma_f32_16x16x32_bf16 v[54:57], v[174:177], v[190:193], v[54:57]
	v_mfma_f32_16x16x32_bf16 v[50:53], v[182:185], v[190:193], v[50:53]
	v_mfma_f32_16x16x32_bf16 v[38:41], v[174:177], v[198:201], v[38:41]
	v_mfma_f32_16x16x32_bf16 v[34:37], v[182:185], v[198:201], v[34:37]
	v_mfma_f32_16x16x32_bf16 v[22:25], v[174:177], v[206:209], v[22:25]
	v_mfma_f32_16x16x32_bf16 v[18:21], v[182:185], v[206:209], v[18:21]
	v_mfma_f32_16x16x32_bf16 v[6:9], v[174:177], v[214:217], v[6:9]
	v_mfma_f32_16x16x32_bf16 v[2:5], v[182:185], v[214:217], v[2:5]
	v_mfma_f32_16x16x32_bf16 v[54:57], v[178:181], v[194:197], v[54:57]
	v_mfma_f32_16x16x32_bf16 v[50:53], v[186:189], v[194:197], v[50:53]
	v_mfma_f32_16x16x32_bf16 v[38:41], v[178:181], v[202:205], v[38:41]
	v_mfma_f32_16x16x32_bf16 v[34:37], v[186:189], v[202:205], v[34:37]
	v_mfma_f32_16x16x32_bf16 v[22:25], v[178:181], v[210:213], v[22:25]
	v_mfma_f32_16x16x32_bf16 v[18:21], v[186:189], v[210:213], v[18:21]
	v_mfma_f32_16x16x32_bf16 v[6:9], v[178:181], v[224:227], v[6:9]
	v_mfma_f32_16x16x32_bf16 v[2:5], v[186:189], v[224:227], v[2:5]
	s_barrier
	s_setprio 0
	s_add_i32 s48, 0, 0x18000
	s_add_i32 s91, 0, 0x1c000
	v_add_u32_e32 v170, s48, v163
	v_add_u32_e32 v186, s91, v163
	ds_read_b128 v[152:155], v170
	ds_read_b128 v[156:159], v170 offset:1024
	ds_read_b128 v[166:169], v170 offset:2048
	ds_read_b128 v[170:173], v170 offset:3072
	ds_read_b128 v[174:177], v186
	ds_read_b128 v[178:181], v186 offset:1024
	ds_read_b128 v[182:185], v186 offset:2048
	ds_read_b128 v[186:189], v186 offset:3072
	s_add_u32 s30, s30, 0x80000
	s_addc_u32 s31, s31, 0
	s_mov_b32 m0, s35
	v_lshl_add_u64 v[228:229], s[30:31], 0, v[0:1]
	ds_read_b128 v[190:193], v165 offset:32768
	ds_read_b128 v[194:197], v165 offset:33792
	ds_read_b128 v[198:201], v165 offset:34816
	ds_read_b128 v[202:205], v165 offset:35840
	ds_read_b128 v[206:209], v165 offset:36864
	ds_read_b128 v[210:213], v165 offset:37888
	ds_read_b128 v[214:217], v165 offset:38912
	ds_read_b128 v[224:227], v165 offset:39936
	global_load_lds_dwordx4 v[228:229], off
	s_mov_b32 m0, s42
	v_lshl_add_u64 v[228:229], s[30:31], 0, v[126:127]
	global_load_lds_dwordx4 v[228:229], off
	s_waitcnt vmcnt(8) lgkmcnt(0)
	s_setprio 1
	s_barrier
	v_mfma_f32_16x16x32_bf16 v[144:147], v[152:155], v[190:193], v[144:147]
	v_mfma_f32_16x16x32_bf16 v[122:125], v[166:169], v[190:193], v[122:125]
	v_mfma_f32_16x16x32_bf16 v[110:113], v[152:155], v[198:201], v[110:113]
	v_mfma_f32_16x16x32_bf16 v[106:109], v[166:169], v[198:201], v[106:109]
	v_mfma_f32_16x16x32_bf16 v[94:97], v[152:155], v[206:209], v[94:97]
	v_mfma_f32_16x16x32_bf16 v[90:93], v[166:169], v[206:209], v[90:93]
	v_mfma_f32_16x16x32_bf16 v[78:81], v[152:155], v[214:217], v[78:81]
	v_mfma_f32_16x16x32_bf16 v[74:77], v[166:169], v[214:217], v[74:77]
	v_mfma_f32_16x16x32_bf16 v[144:147], v[156:159], v[194:197], v[144:147]
	v_mfma_f32_16x16x32_bf16 v[122:125], v[170:173], v[194:197], v[122:125]
	v_mfma_f32_16x16x32_bf16 v[110:113], v[156:159], v[202:205], v[110:113]
	v_mfma_f32_16x16x32_bf16 v[106:109], v[170:173], v[202:205], v[106:109]
	v_mfma_f32_16x16x32_bf16 v[94:97], v[156:159], v[210:213], v[94:97]
	v_mfma_f32_16x16x32_bf16 v[90:93], v[170:173], v[210:213], v[90:93]
	v_mfma_f32_16x16x32_bf16 v[78:81], v[156:159], v[224:227], v[78:81]
	v_mfma_f32_16x16x32_bf16 v[74:77], v[170:173], v[224:227], v[74:77]
	v_mfma_f32_16x16x32_bf16 v[118:121], v[174:177], v[190:193], v[118:121]
	v_mfma_f32_16x16x32_bf16 v[114:117], v[182:185], v[190:193], v[114:117]
	v_mfma_f32_16x16x32_bf16 v[102:105], v[174:177], v[198:201], v[102:105]
	v_mfma_f32_16x16x32_bf16 v[98:101], v[182:185], v[198:201], v[98:101]
	v_mfma_f32_16x16x32_bf16 v[86:89], v[174:177], v[206:209], v[86:89]
	v_mfma_f32_16x16x32_bf16 v[82:85], v[182:185], v[206:209], v[82:85]
	v_mfma_f32_16x16x32_bf16 v[70:73], v[174:177], v[214:217], v[70:73]
	v_mfma_f32_16x16x32_bf16 v[66:69], v[182:185], v[214:217], v[66:69]
	v_mfma_f32_16x16x32_bf16 v[118:121], v[178:181], v[194:197], v[118:121]
	v_mfma_f32_16x16x32_bf16 v[114:117], v[186:189], v[194:197], v[114:117]
	v_mfma_f32_16x16x32_bf16 v[102:105], v[178:181], v[202:205], v[102:105]
	v_mfma_f32_16x16x32_bf16 v[98:101], v[186:189], v[202:205], v[98:101]
	v_mfma_f32_16x16x32_bf16 v[86:89], v[178:181], v[210:213], v[86:89]
	v_mfma_f32_16x16x32_bf16 v[82:85], v[186:189], v[210:213], v[82:85]
	v_mfma_f32_16x16x32_bf16 v[70:73], v[178:181], v[224:227], v[70:73]
	v_mfma_f32_16x16x32_bf16 v[66:69], v[186:189], v[224:227], v[66:69]
	s_barrier
; #define PG8_STAGE(bufoff, gbase, voff) do { _Pragma("unroll") for (int _i = 0; _i < 2; ++_i) \
;         __builtin_amdgcn_global_load_lds((const unsigned*)((const char*)(gbase) + (voff)[_i]), (PG8_LAS unsigned*)(lds + (bufoff) + ldsw + _i * 8192), 16, 0, 0); } while (0)
; #define PG8_LDA(dst, b, h) do { _Pragma("unroll") for (int m = 0; m < 4; ++m) _Pragma("unroll") for (int k = 0; k < 2; ++k) dst[m][k] = *(const PG8_LAS bf16x8*)(lds + PG8_SA(b, h) + aoff + m * 2048 + k * 1024); } while (0)
; #define PG8_WAIT_V(n) asm volatile("s_waitcnt vmcnt(" #n ")" ::: "memory")
; template <class Epi, class Sched, bool ALIGN_EPI = false, bool SP2 = false>
; __device__ __forceinline__ void gemm_phase(PG8_LAS unsigned char* lds, const Gemm g, const Sched& S, const Epi& E) {
;     ...
;         for (int t = 0; t < nt; t += 2) {
;             if constexpr (Epi::HAS_MID) { if (t == Epi::MID0 || t == Epi::MID1) E.mid(acc, cur, wr, wc, fr, fq, t == Epi::MID0 ? 0 : 1); }
;             const bool last = (t == nt - 2);
;             const char* a1 = cA + (size_t)(t + 1) * kstep;
;             const char* a2 = last ? nA : cA + (size_t)(t + 2) * kstep; const char* b2 = last ? nB : cB + (size_t)(t + 2) * kstep;
;             const char* a3 = a2 + kstep; const char* b3 = b2 + kstep;
;             if (last && has_next) S.a_ready(nxt);
;             if constexpr (SP2) {
;             PG8_LDB(B0, 0, 0); PG8_LDB(B1, 0, 1); PG8_SCHED; PG8_LDA(At, 0, 0); PG8_STAGE(PG8_SA(1, 1), a1 + hstep, voffA);
;             PG8_WAIT_V(8); PG8_WAIT_L(0); PG8_BAR; PG8_MMA(0, 0, At, B0); PG8_MMA(0, 1, At, B1); PG8_BAR; PG8_SCHED;
;             PG8_LDA(At, 0, 1); PG8_STAGE(PG8_SB(0, 0), b2, voffB); PG8_STAGE(PG8_SB(0, 1), b2 + hstep, voffB); PG8_STAGE(PG8_SA(0, 0), a2, voffA);
;             PG8_WAIT_V(8); PG8_WAIT_L(0); PG8_BAR; PG8_MMA(1, 0, At, B0); PG8_MMA(1, 1, At, B1); PG8_BAR; PG8_SCHED;
;             PG8_LDB(B0, 1, 0); PG8_LDB(B1, 1, 1); PG8_SCHED; PG8_LDA(At, 1, 0); PG8_STAGE(PG8_SA(0, 1), a2 + hstep, voffA);
;             PG8_WAIT_V(8); PG8_WAIT_L(0); PG8_BAR; PG8_MMA(0, 0, At, B0); PG8_MMA(0, 1, At, B1); PG8_BAR; PG8_SCHED;
;             PG8_LDA(At, 1, 1); PG8_STAGE(PG8_SB(1, 0), b3, voffB); PG8_STAGE(PG8_SB(1, 1), b3 + hstep, voffB); PG8_STAGE(PG8_SA(1, 0), a3, voffA);
;             PG8_WAIT_V(8); PG8_WAIT_L(0); PG8_BAR; PG8_MMA(1, 0, At, B0); PG8_MMA(1, 1, At, B1); PG8_BAR; PG8_SCHED;
	s_setprio 0
	s_add_i32 s30, s48, s12
	v_lshl_add_u64 v[160:161], v[160:161], 0, s[64:65]
	s_mov_b32 m0, s30
	ds_read_b128 v[190:193], v165 offset:49152
	ds_read_b128 v[194:197], v165 offset:50176
	ds_read_b128 v[198:201], v165 offset:51200
	ds_read_b128 v[202:205], v165 offset:52224
	ds_read_b128 v[206:209], v165 offset:53248
	ds_read_b128 v[210:213], v165 offset:54272
	ds_read_b128 v[214:217], v165 offset:55296
	ds_read_b128 v[224:227], v165 offset:56320
	global_load_lds_dwordx4 v[160:161], off
	s_add_i32 m0, s30, 0x2000
	s_add_u32 s28, s28, 0x80080
	v_lshl_add_u64 v[160:161], v[218:219], 0, s[64:65]
	s_addc_u32 s29, s29, 0
	s_add_i32 s30, s91, s12
	global_load_lds_dwordx4 v[160:161], off
	s_mov_b32 m0, s30
	v_lshl_add_u64 v[160:161], s[28:29], 0, v[0:1]
	global_load_lds_dwordx4 v[160:161], off
	s_add_i32 m0, s30, 0x2000
	v_lshl_add_u64 v[160:161], s[28:29], 0, v[126:127]
	global_load_lds_dwordx4 v[160:161], off
	s_mov_b32 m0, s43
	v_lshl_add_u64 v[160:161], v[220:221], 0, s[64:65]
	global_load_lds_dwordx4 v[160:161], off
	s_mov_b32 m0, s76
	v_lshl_add_u64 v[160:161], v[222:223], 0, s[64:65]
	global_load_lds_dwordx4 v[160:161], off
	s_waitcnt vmcnt(8) lgkmcnt(0)
	s_setprio 1
	s_barrier
	v_mfma_f32_16x16x32_bf16 v[62:65], v[152:155], v[190:193], v[62:65]
	v_mfma_f32_16x16x32_bf16 v[58:61], v[166:169], v[190:193], v[58:61]
	v_mfma_f32_16x16x32_bf16 v[46:49], v[152:155], v[198:201], v[46:49]
	v_mfma_f32_16x16x32_bf16 v[42:45], v[166:169], v[198:201], v[42:45]
	v_mfma_f32_16x16x32_bf16 v[30:33], v[152:155], v[206:209], v[30:33]
	v_mfma_f32_16x16x32_bf16 v[26:29], v[166:169], v[206:209], v[26:29]
	v_mfma_f32_16x16x32_bf16 v[14:17], v[152:155], v[214:217], v[14:17]
	v_mfma_f32_16x16x32_bf16 v[10:13], v[166:169], v[214:217], v[10:13]
	v_mfma_f32_16x16x32_bf16 v[62:65], v[156:159], v[194:197], v[62:65]
	v_mfma_f32_16x16x32_bf16 v[58:61], v[170:173], v[194:197], v[58:61]
	v_mfma_f32_16x16x32_bf16 v[46:49], v[156:159], v[202:205], v[46:49]
	v_mfma_f32_16x16x32_bf16 v[42:45], v[170:173], v[202:205], v[42:45]
	v_mfma_f32_16x16x32_bf16 v[30:33], v[156:159], v[210:213], v[30:33]
	v_mfma_f32_16x16x32_bf16 v[26:29], v[170:173], v[210:213], v[26:29]
	v_mfma_f32_16x16x32_bf16 v[14:17], v[156:159], v[224:227], v[14:17]
	v_mfma_f32_16x16x32_bf16 v[10:13], v[170:173], v[224:227], v[10:13]
	v_mfma_f32_16x16x32_bf16 v[54:57], v[174:177], v[190:193], v[54:57]
	v_mfma_f32_16x16x32_bf16 v[50:53], v[182:185], v[190:193], v[50:53]
	v_mfma_f32_16x16x32_bf16 v[38:41], v[174:177], v[198:201], v[38:41]
	v_mfma_f32_16x16x32_bf16 v[34:37], v[182:185], v[198:201], v[34:37]
	v_mfma_f32_16x16x32_bf16 v[22:25], v[174:177], v[206:209], v[22:25]
	v_mfma_f32_16x16x32_bf16 v[18:21], v[182:185], v[206:209], v[18:21]
	v_mfma_f32_16x16x32_bf16 v[6:9], v[174:177], v[214:217], v[6:9]
	v_mfma_f32_16x16x32_bf16 v[2:5], v[182:185], v[214:217], v[2:5]
	v_mfma_f32_16x16x32_bf16 v[54:57], v[178:181], v[194:197], v[54:57]
	v_mfma_f32_16x16x32_bf16 v[50:53], v[186:189], v[194:197], v[50:53]
	v_mfma_f32_16x16x32_bf16 v[38:41], v[178:181], v[202:205], v[38:41]
	v_mfma_f32_16x16x32_bf16 v[34:37], v[186:189], v[202:205], v[34:37]
	v_mfma_f32_16x16x32_bf16 v[22:25], v[178:181], v[210:213], v[22:25]
	v_mfma_f32_16x16x32_bf16 v[18:21], v[186:189], v[210:213], v[18:21]
	v_mfma_f32_16x16x32_bf16 v[6:9], v[178:181], v[224:227], v[6:9]
	v_mfma_f32_16x16x32_bf16 v[2:5], v[186:189], v[224:227], v[2:5]
	s_barrier
	s_setprio 0
	s_add_i32 s87, s87, 2
	s_add_u32 s8, s8, 0x100
	s_addc_u32 s9, s9, 0
	s_add_u32 s83, s83, 0x100
	s_addc_u32 s86, s86, 0
	s_cmp_gt_u32 s87, 29
	s_cbranch_scc0 .LBB0_808
	s_and_b64 vcc, exec, s[18:19]
	s_cbranch_vccz .LBB0_811
	s_barrier

; #define PG8_STAGE(bufoff, gbase, voff) do { _Pragma("unroll") for (int _i = 0; _i < 2; ++_i) \
;         __builtin_amdgcn_global_load_lds((const unsigned*)((const char*)(gbase) + (voff)[_i]), (PG8_LAS unsigned*)(lds + (bufoff) + ldsw + _i * 8192), 16, 0, 0); } while (0)
; #define PG8_LDA(dst, b, h) do { _Pragma("unroll") for (int m = 0; m < 4; ++m) _Pragma("unroll") for (int k = 0; k < 2; ++k) dst[m][k] = *(const PG8_LAS bf16x8*)(lds + PG8_SA(b, h) + aoff + m * 2048 + k * 1024); } while (0)
; #define PG8_LDB(dst, b, h) do { _Pragma("unroll") for (int n = 0; n < 2; ++n) _Pragma("unroll") for (int k = 0; k < 2; ++k) dst[n][k] = *(const PG8_LAS bf16x8*)(lds + PG8_SB(b, h) + boff + n * 2048 + k * 1024); } while (0)
; #define PG8_BAR __builtin_amdgcn_s_barrier()
; template <class Epi, class Sched, bool ALIGN_EPI = false, bool SP2 = false>
; __device__ __forceinline__ void gemm_phase(PG8_LAS unsigned char* lds, const Gemm g, const Sched& S, const Epi& E) {
;     ...
;             const bool last = (t == nt - 2);
;             const char* a1 = cA + (size_t)(t + 1) * kstep;
;             const char* a2 = last ? nA : cA + (size_t)(t + 2) * kstep; const char* b2 = last ? nB : cB + (size_t)(t + 2) * kstep;
;             const char* a3 = a2 + kstep; const char* b3 = b2 + kstep;
;             if (last && has_next) S.a_ready(nxt);
;             if constexpr (SP2) {
;             PG8_LDB(B0, 0, 0); PG8_LDB(B1, 0, 1); PG8_SCHED; PG8_LDA(At, 0, 0); PG8_STAGE(PG8_SA(1, 1), a1 + hstep, voffA);
;             PG8_WAIT_V(8); PG8_WAIT_L(0); PG8_BAR; PG8_MMA(0, 0, At, B0); PG8_MMA(0, 1, At, B1); PG8_BAR; PG8_SCHED;
;             PG8_LDA(At, 0, 1); PG8_STAGE(PG8_SB(0, 0), b2, voffB); PG8_STAGE(PG8_SB(0, 1), b2 + hstep, voffB); PG8_STAGE(PG8_SA(0, 0), a2, voffA);
;             PG8_WAIT_V(8); PG8_WAIT_L(0); PG8_BAR; PG8_MMA(1, 0, At, B0); PG8_MMA(1, 1, At, B1); PG8_BAR; PG8_SCHED;
;             PG8_LDB(B0, 1, 0); PG8_LDB(B1, 1, 1); PG8_SCHED; PG8_LDA(At, 1, 0); PG8_STAGE(PG8_SA(0, 1), a2 + hstep, voffA);
;             PG8_WAIT_V(8); PG8_WAIT_L(0); PG8_BAR; PG8_MMA(0, 0, At, B0); PG8_MMA(0, 1, At, B1); PG8_BAR; PG8_SCHED;
;             PG8_LDA(At, 1, 1); PG8_STAGE(PG8_SB(1, 0), b3, voffB); PG8_STAGE(PG8_SB(1, 1), b3 + hstep, voffB); PG8_STAGE(PG8_SA(1, 0), a3, voffA);
;             PG8_WAIT_V(8); PG8_WAIT_L(0); PG8_BAR; PG8_MMA(1, 0, At, B0); PG8_MMA(1, 1, At, B1); PG8_BAR; PG8_SCHED;
.LBB0_910:
	s_add_u32 s28, s0, 0xfff80080
	s_addc_u32 s29, s1, -1
	s_add_i32 s48, 0, 0x10000
	s_cmp_eq_u32 s81, 28
	s_cselect_b32 s31, s21, s29
	s_cselect_b32 s30, s35, s28
	s_cselect_b32 s29, s23, s67
	s_cselect_b32 s28, s40, s41
	s_add_i32 s91, 0, 0x14000
	v_add_u32_e32 v164, s48, v179
	v_add_u32_e32 v176, s91, v179
	ds_read_b128 v[152:155], v164
	ds_read_b128 v[156:159], v164 offset:1024
	ds_read_b128 v[160:163], v164 offset:2048
	ds_read_b128 v[164:167], v164 offset:3072
	ds_read_b128 v[168:171], v176
	ds_read_b128 v[172:175], v176 offset:1024
	ds_read_b128 v[182:185], v176 offset:2048
	ds_read_b128 v[186:189], v176 offset:3072
	v_lshl_add_u64 v[176:177], s[0:1], 0, v[148:149]
	s_add_i32 m0, s43, 0xc000
	ds_read_b128 v[190:193], v181
	ds_read_b128 v[194:197], v181 offset:1024
	ds_read_b128 v[198:201], v181 offset:2048
	ds_read_b128 v[202:205], v181 offset:3072
	ds_read_b128 v[206:209], v181 offset:4096
	ds_read_b128 v[210:213], v181 offset:5120
	ds_read_b128 v[214:217], v181 offset:6144
	ds_read_b128 v[224:227], v181 offset:7168
	global_load_lds_dwordx4 v[176:177], off
	s_add_i32 m0, s43, 0xe000
	v_lshl_add_u64 v[176:177], s[0:1], 0, v[150:151]
	global_load_lds_dwordx4 v[176:177], off
	s_waitcnt vmcnt(8) lgkmcnt(0)
	s_setprio 1
	s_barrier
	v_mfma_f32_16x16x32_bf16 v[74:77], v[152:155], v[190:193], v[74:77]
	v_mfma_f32_16x16x32_bf16 v[78:81], v[160:163], v[190:193], v[78:81]
	v_mfma_f32_16x16x32_bf16 v[102:105], v[152:155], v[198:201], v[102:105]
	v_mfma_f32_16x16x32_bf16 v[106:109], v[160:163], v[198:201], v[106:109]
	v_mfma_f32_16x16x32_bf16 v[122:125], v[152:155], v[206:209], v[122:125]
	v_mfma_f32_16x16x32_bf16 v[144:147], v[160:163], v[206:209], v[144:147]
	v_mfma_f32_16x16x32_bf16 v[90:93], v[152:155], v[214:217], v[90:93]
	v_mfma_f32_16x16x32_bf16 v[86:89], v[160:163], v[214:217], v[86:89]
	v_mfma_f32_16x16x32_bf16 v[74:77], v[156:159], v[194:197], v[74:77]
	v_mfma_f32_16x16x32_bf16 v[78:81], v[164:167], v[194:197], v[78:81]
	v_mfma_f32_16x16x32_bf16 v[102:105], v[156:159], v[202:205], v[102:105]
	v_mfma_f32_16x16x32_bf16 v[106:109], v[164:167], v[202:205], v[106:109]
	v_mfma_f32_16x16x32_bf16 v[122:125], v[156:159], v[210:213], v[122:125]
	v_mfma_f32_16x16x32_bf16 v[144:147], v[164:167], v[210:213], v[144:147]
	v_mfma_f32_16x16x32_bf16 v[90:93], v[156:159], v[224:227], v[90:93]
	v_mfma_f32_16x16x32_bf16 v[86:89], v[164:167], v[224:227], v[86:89]
	v_mfma_f32_16x16x32_bf16 v[82:85], v[168:171], v[190:193], v[82:85]
	v_mfma_f32_16x16x32_bf16 v[94:97], v[182:185], v[190:193], v[94:97]
	v_mfma_f32_16x16x32_bf16 v[110:113], v[168:171], v[198:201], v[110:113]
	v_mfma_f32_16x16x32_bf16 v[118:121], v[182:185], v[198:201], v[118:121]
	v_mfma_f32_16x16x32_bf16 v[114:117], v[168:171], v[206:209], v[114:117]
	v_mfma_f32_16x16x32_bf16 v[98:101], v[182:185], v[206:209], v[98:101]
	v_mfma_f32_16x16x32_bf16 v[70:73], v[168:171], v[214:217], v[70:73]
	v_mfma_f32_16x16x32_bf16 v[66:69], v[182:185], v[214:217], v[66:69]
	v_mfma_f32_16x16x32_bf16 v[82:85], v[172:175], v[194:197], v[82:85]
	v_mfma_f32_16x16x32_bf16 v[94:97], v[186:189], v[194:197], v[94:97]
	v_mfma_f32_16x16x32_bf16 v[110:113], v[172:175], v[202:205], v[110:113]
	v_mfma_f32_16x16x32_bf16 v[118:121], v[186:189], v[202:205], v[118:121]
	v_mfma_f32_16x16x32_bf16 v[114:117], v[172:175], v[210:213], v[114:117]
	v_mfma_f32_16x16x32_bf16 v[98:101], v[186:189], v[210:213], v[98:101]
	v_mfma_f32_16x16x32_bf16 v[70:73], v[172:175], v[224:227], v[70:73]
	v_mfma_f32_16x16x32_bf16 v[66:69], v[186:189], v[224:227], v[66:69]
	s_barrier
	s_setprio 0
	s_add_i32 s48, s48, s42
	v_lshl_add_u64 v[176:177], s[28:29], 0, v[0:1]
	s_mov_b32 m0, s48
	ds_read_b128 v[190:193], v181 offset:16384
	ds_read_b128 v[194:197], v181 offset:17408
	ds_read_b128 v[198:201], v181 offset:18432
	ds_read_b128 v[202:205], v181 offset:19456
	ds_read_b128 v[206:209], v181 offset:20480
	ds_read_b128 v[210:213], v181 offset:21504
	ds_read_b128 v[214:217], v181 offset:22528
	ds_read_b128 v[224:227], v181 offset:23552
	global_load_lds_dwordx4 v[176:177], off
	s_add_i32 m0, s48, 0x2000
	s_add_u32 vcc_lo, s28, 0x80000
	v_lshl_add_u64 v[218:219], s[28:29], 0, v[126:127]
	s_addc_u32 vcc_hi, s29, 0
	s_add_i32 s48, s91, s42
	global_load_lds_dwordx4 v[218:219], off
	v_lshl_add_u64 v[220:221], vcc, 0, v[0:1]
	s_mov_b32 m0, s48
	v_lshl_add_u64 v[222:223], s[30:31], 0, v[126:127]
	global_load_lds_dwordx4 v[220:221], off
	s_add_i32 m0, s48, 0x2000
	v_lshl_add_u64 v[220:221], vcc, 0, v[126:127]
	global_load_lds_dwordx4 v[220:221], off
	s_mov_b32 m0, s43
	v_lshl_add_u64 v[220:221], s[30:31], 0, v[0:1]
	global_load_lds_dwordx4 v[220:221], off
	s_mov_b32 m0, s76
	s_nop 0
	global_load_lds_dwordx4 v[222:223], off
	s_waitcnt vmcnt(8) lgkmcnt(0)
	s_setprio 1
	s_barrier
; #define PG8_STAGE(bufoff, gbase, voff) do { _Pragma("unroll") for (int _i = 0; _i < 2; ++_i) \
;         __builtin_amdgcn_global_load_lds((const unsigned*)((const char*)(gbase) + (voff)[_i]), (PG8_LAS unsigned*)(lds + (bufoff) + ldsw + _i * 8192), 16, 0, 0); } while (0)
; #define PG8_LDA(dst, b, h) do { _Pragma("unroll") for (int m = 0; m < 4; ++m) _Pragma("unroll") for (int k = 0; k < 2; ++k) dst[m][k] = *(const PG8_LAS bf16x8*)(lds + PG8_SA(b, h) + aoff + m * 2048 + k * 1024); } while (0)
; #define PG8_LDB(dst, b, h) do { _Pragma("unroll") for (int n = 0; n < 2; ++n) _Pragma("unroll") for (int k = 0; k < 2; ++k) dst[n][k] = *(const PG8_LAS bf16x8*)(lds + PG8_SB(b, h) + boff + n * 2048 + k * 1024); } while (0)
; #define PG8_MMA(ai, bj, At, Bt) do { __builtin_amdgcn_s_setprio(1); _Pragma("unroll") for (int m = 0; m < 4; ++m) _Pragma("unroll") for (int n = 0; n < 2; ++n) _Pragma("unroll") for (int k = 0; k < 2; ++k) \
;         acc[ai][bj][m][n] = __builtin_amdgcn_mfma_f32_16x16x32_bf16(Bt[n][k], At[m][k], acc[ai][bj][m][n], 0, 0, 0); __builtin_amdgcn_s_setprio(0); } while (0)
; #define PG8_WAIT_V(n) asm volatile("s_waitcnt vmcnt(" #n ")" ::: "memory")
; #define PG8_WAIT_L(n) asm volatile("s_waitcnt lgkmcnt(" #n ")" ::: "memory")
; #define PG8_BAR __builtin_amdgcn_s_barrier()
; #define PG8_SCHED __builtin_amdgcn_sched_barrier(0)
; template <class Epi, class Sched, bool ALIGN_EPI = false, bool SP2 = false>
; __device__ __forceinline__ void gemm_phase(PG8_LAS unsigned char* lds, const Gemm g, const Sched& S, const Epi& E) {
;     ...
;             PG8_WAIT_V(8); PG8_WAIT_L(0); PG8_BAR; PG8_MMA(0, 0, At, B0); PG8_MMA(0, 1, At, B1); PG8_BAR; PG8_SCHED;
;             PG8_LDA(At, 0, 1); PG8_STAGE(PG8_SB(0, 0), b2, voffB); PG8_STAGE(PG8_SB(0, 1), b2 + hstep, voffB); PG8_STAGE(PG8_SA(0, 0), a2, voffA);
;             PG8_WAIT_V(8); PG8_WAIT_L(0); PG8_BAR; PG8_MMA(1, 0, At, B0); PG8_MMA(1, 1, At, B1); PG8_BAR; PG8_SCHED;
;             PG8_LDB(B0, 1, 0); PG8_LDB(B1, 1, 1); PG8_SCHED; PG8_LDA(At, 1, 0); PG8_STAGE(PG8_SA(0, 1), a2 + hstep, voffA);
;             PG8_WAIT_V(8); PG8_WAIT_L(0); PG8_BAR; PG8_MMA(0, 0, At, B0); PG8_MMA(0, 1, At, B1); PG8_BAR; PG8_SCHED;
	v_mfma_f32_16x16x32_bf16 v[62:65], v[152:155], v[190:193], v[62:65]
	v_mfma_f32_16x16x32_bf16 v[58:61], v[160:163], v[190:193], v[58:61]
	v_mfma_f32_16x16x32_bf16 v[46:49], v[152:155], v[198:201], v[46:49]
	v_mfma_f32_16x16x32_bf16 v[42:45], v[160:163], v[198:201], v[42:45]
	v_mfma_f32_16x16x32_bf16 v[30:33], v[152:155], v[206:209], v[30:33]
	v_mfma_f32_16x16x32_bf16 v[26:29], v[160:163], v[206:209], v[26:29]
	v_mfma_f32_16x16x32_bf16 v[14:17], v[152:155], v[214:217], v[14:17]
	v_mfma_f32_16x16x32_bf16 v[10:13], v[160:163], v[214:217], v[10:13]
	v_mfma_f32_16x16x32_bf16 v[62:65], v[156:159], v[194:197], v[62:65]
	v_mfma_f32_16x16x32_bf16 v[58:61], v[164:167], v[194:197], v[58:61]
	v_mfma_f32_16x16x32_bf16 v[46:49], v[156:159], v[202:205], v[46:49]
	v_mfma_f32_16x16x32_bf16 v[42:45], v[164:167], v[202:205], v[42:45]
	v_mfma_f32_16x16x32_bf16 v[30:33], v[156:159], v[210:213], v[30:33]
	v_mfma_f32_16x16x32_bf16 v[26:29], v[164:167], v[210:213], v[26:29]
	v_mfma_f32_16x16x32_bf16 v[14:17], v[156:159], v[224:227], v[14:17]
	v_mfma_f32_16x16x32_bf16 v[10:13], v[164:167], v[224:227], v[10:13]
	v_mfma_f32_16x16x32_bf16 v[54:57], v[168:171], v[190:193], v[54:57]
	v_mfma_f32_16x16x32_bf16 v[50:53], v[182:185], v[190:193], v[50:53]
	v_mfma_f32_16x16x32_bf16 v[38:41], v[168:171], v[198:201], v[38:41]
	v_mfma_f32_16x16x32_bf16 v[34:37], v[182:185], v[198:201], v[34:37]
	v_mfma_f32_16x16x32_bf16 v[22:25], v[168:171], v[206:209], v[22:25]
	v_mfma_f32_16x16x32_bf16 v[18:21], v[182:185], v[206:209], v[18:21]
	v_mfma_f32_16x16x32_bf16 v[6:9], v[168:171], v[214:217], v[6:9]
	v_mfma_f32_16x16x32_bf16 v[2:5], v[182:185], v[214:217], v[2:5]
	v_mfma_f32_16x16x32_bf16 v[54:57], v[172:175], v[194:197], v[54:57]
	v_mfma_f32_16x16x32_bf16 v[50:53], v[186:189], v[194:197], v[50:53]
	v_mfma_f32_16x16x32_bf16 v[38:41], v[172:175], v[202:205], v[38:41]
	v_mfma_f32_16x16x32_bf16 v[34:37], v[186:189], v[202:205], v[34:37]
	v_mfma_f32_16x16x32_bf16 v[22:25], v[172:175], v[210:213], v[22:25]
	v_mfma_f32_16x16x32_bf16 v[18:21], v[186:189], v[210:213], v[18:21]
	v_mfma_f32_16x16x32_bf16 v[6:9], v[172:175], v[224:227], v[6:9]
	v_mfma_f32_16x16x32_bf16 v[2:5], v[186:189], v[224:227], v[2:5]
	s_barrier
	s_setprio 0
	s_add_i32 s48, 0, 0x18000
	s_add_i32 s91, 0, 0x1c000
	v_add_u32_e32 v164, s48, v179
	v_add_u32_e32 v186, s91, v179
	ds_read_b128 v[152:155], v164
	ds_read_b128 v[156:159], v164 offset:1024
	ds_read_b128 v[160:163], v164 offset:2048
	ds_read_b128 v[164:167], v164 offset:3072
	ds_read_b128 v[168:171], v186
	ds_read_b128 v[172:175], v186 offset:1024
	ds_read_b128 v[182:185], v186 offset:2048
	ds_read_b128 v[186:189], v186 offset:3072
	s_add_u32 s30, s30, 0x80000
	s_addc_u32 s31, s31, 0
	s_mov_b32 m0, s82
	v_lshl_add_u64 v[228:229], s[30:31], 0, v[0:1]
	ds_read_b128 v[190:193], v181 offset:32768
	ds_read_b128 v[194:197], v181 offset:33792
	ds_read_b128 v[198:201], v181 offset:34816
	ds_read_b128 v[202:205], v181 offset:35840
	ds_read_b128 v[206:209], v181 offset:36864
	ds_read_b128 v[210:213], v181 offset:37888
	ds_read_b128 v[214:217], v181 offset:38912
	ds_read_b128 v[224:227], v181 offset:39936
	global_load_lds_dwordx4 v[228:229], off
	s_mov_b32 m0, s83
	v_lshl_add_u64 v[228:229], s[30:31], 0, v[126:127]
	global_load_lds_dwordx4 v[228:229], off
	s_waitcnt vmcnt(8) lgkmcnt(0)
	s_setprio 1
	s_barrier
	v_mfma_f32_16x16x32_bf16 v[74:77], v[152:155], v[190:193], v[74:77]
	v_mfma_f32_16x16x32_bf16 v[78:81], v[160:163], v[190:193], v[78:81]
	v_mfma_f32_16x16x32_bf16 v[102:105], v[152:155], v[198:201], v[102:105]
	v_mfma_f32_16x16x32_bf16 v[106:109], v[160:163], v[198:201], v[106:109]
	v_mfma_f32_16x16x32_bf16 v[122:125], v[152:155], v[206:209], v[122:125]
	v_mfma_f32_16x16x32_bf16 v[144:147], v[160:163], v[206:209], v[144:147]
	v_mfma_f32_16x16x32_bf16 v[90:93], v[152:155], v[214:217], v[90:93]
	v_mfma_f32_16x16x32_bf16 v[86:89], v[160:163], v[214:217], v[86:89]
	v_mfma_f32_16x16x32_bf16 v[74:77], v[156:159], v[194:197], v[74:77]
	v_mfma_f32_16x16x32_bf16 v[78:81], v[164:167], v[194:197], v[78:81]
	v_mfma_f32_16x16x32_bf16 v[102:105], v[156:159], v[202:205], v[102:105]
	v_mfma_f32_16x16x32_bf16 v[106:109], v[164:167], v[202:205], v[106:109]
	v_mfma_f32_16x16x32_bf16 v[122:125], v[156:159], v[210:213], v[122:125]
	v_mfma_f32_16x16x32_bf16 v[144:147], v[164:167], v[210:213], v[144:147]
	v_mfma_f32_16x16x32_bf16 v[90:93], v[156:159], v[224:227], v[90:93]
	v_mfma_f32_16x16x32_bf16 v[86:89], v[164:167], v[224:227], v[86:89]
	v_mfma_f32_16x16x32_bf16 v[82:85], v[168:171], v[190:193], v[82:85]
	v_mfma_f32_16x16x32_bf16 v[94:97], v[182:185], v[190:193], v[94:97]
	v_mfma_f32_16x16x32_bf16 v[110:113], v[168:171], v[198:201], v[110:113]
	v_mfma_f32_16x16x32_bf16 v[118:121], v[182:185], v[198:201], v[118:121]
	v_mfma_f32_16x16x32_bf16 v[114:117], v[168:171], v[206:209], v[114:117]
	v_mfma_f32_16x16x32_bf16 v[98:101], v[182:185], v[206:209], v[98:101]
	v_mfma_f32_16x16x32_bf16 v[70:73], v[168:171], v[214:217], v[70:73]
	v_mfma_f32_16x16x32_bf16 v[66:69], v[182:185], v[214:217], v[66:69]
	v_mfma_f32_16x16x32_bf16 v[82:85], v[172:175], v[194:197], v[82:85]
	v_mfma_f32_16x16x32_bf16 v[94:97], v[186:189], v[194:197], v[94:97]
	v_mfma_f32_16x16x32_bf16 v[110:113], v[172:175], v[202:205], v[110:113]
	v_mfma_f32_16x16x32_bf16 v[118:121], v[186:189], v[202:205], v[118:121]
	v_mfma_f32_16x16x32_bf16 v[114:117], v[172:175], v[210:213], v[114:117]
	v_mfma_f32_16x16x32_bf16 v[98:101], v[186:189], v[210:213], v[98:101]
	v_mfma_f32_16x16x32_bf16 v[70:73], v[172:175], v[224:227], v[70:73]
	v_mfma_f32_16x16x32_bf16 v[66:69], v[186:189], v[224:227], v[66:69]
	s_barrier
; #define PG8_STAGE(bufoff, gbase, voff) do { _Pragma("unroll") for (int _i = 0; _i < 2; ++_i) \
;         __builtin_amdgcn_global_load_lds((const unsigned*)((const char*)(gbase) + (voff)[_i]), (PG8_LAS unsigned*)(lds + (bufoff) + ldsw + _i * 8192), 16, 0, 0); } while (0)
; #define PG8_LDA(dst, b, h) do { _Pragma("unroll") for (int m = 0; m < 4; ++m) _Pragma("unroll") for (int k = 0; k < 2; ++k) dst[m][k] = *(const PG8_LAS bf16x8*)(lds + PG8_SA(b, h) + aoff + m * 2048 + k * 1024); } while (0)
; #define PG8_WAIT_V(n) asm volatile("s_waitcnt vmcnt(" #n ")" ::: "memory")
; template <class Epi, class Sched, bool ALIGN_EPI = false, bool SP2 = false>
; __device__ __forceinline__ void gemm_phase(PG8_LAS unsigned char* lds, const Gemm g, const Sched& S, const Epi& E) {
;     ...
;         for (int t = 0; t < nt; t += 2) {
;             if constexpr (Epi::HAS_MID) { if (t == Epi::MID0 || t == Epi::MID1) E.mid(acc, cur, wr, wc, fr, fq, t == Epi::MID0 ? 0 : 1); }
;             const bool last = (t == nt - 2);
;             const char* a1 = cA + (size_t)(t + 1) * kstep;
;             const char* a2 = last ? nA : cA + (size_t)(t + 2) * kstep; const char* b2 = last ? nB : cB + (size_t)(t + 2) * kstep;
;             const char* a3 = a2 + kstep; const char* b3 = b2 + kstep;
;             if (last && has_next) S.a_ready(nxt);
;             if constexpr (SP2) {
;             PG8_LDB(B0, 0, 0); PG8_LDB(B1, 0, 1); PG8_SCHED; PG8_LDA(At, 0, 0); PG8_STAGE(PG8_SA(1, 1), a1 + hstep, voffA);
;             PG8_WAIT_V(8); PG8_WAIT_L(0); PG8_BAR; PG8_MMA(0, 0, At, B0); PG8_MMA(0, 1, At, B1); PG8_BAR; PG8_SCHED;
;             PG8_LDA(At, 0, 1); PG8_STAGE(PG8_SB(0, 0), b2, voffB); PG8_STAGE(PG8_SB(0, 1), b2 + hstep, voffB); PG8_STAGE(PG8_SA(0, 0), a2, voffA);
;             PG8_WAIT_V(8); PG8_WAIT_L(0); PG8_BAR; PG8_MMA(1, 0, At, B0); PG8_MMA(1, 1, At, B1); PG8_BAR; PG8_SCHED;
;             PG8_LDB(B0, 1, 0); PG8_LDB(B1, 1, 1); PG8_SCHED; PG8_LDA(At, 1, 0); PG8_STAGE(PG8_SA(0, 1), a2 + hstep, voffA);
;             PG8_WAIT_V(8); PG8_WAIT_L(0); PG8_BAR; PG8_MMA(0, 0, At, B0); PG8_MMA(0, 1, At, B1); PG8_BAR; PG8_SCHED;
;             PG8_LDA(At, 1, 1); PG8_STAGE(PG8_SB(1, 0), b3, voffB); PG8_STAGE(PG8_SB(1, 1), b3 + hstep, voffB); PG8_STAGE(PG8_SA(1, 0), a3, voffA);
;             PG8_WAIT_V(8); PG8_WAIT_L(0); PG8_BAR; PG8_MMA(1, 0, At, B0); PG8_MMA(1, 1, At, B1); PG8_BAR; PG8_SCHED;
	s_setprio 0
	s_add_i32 s30, s48, s42
	v_lshl_add_u64 v[176:177], v[176:177], 0, s[64:65]
	s_mov_b32 m0, s30
	ds_read_b128 v[190:193], v181 offset:49152
	ds_read_b128 v[194:197], v181 offset:50176
	ds_read_b128 v[198:201], v181 offset:51200
	ds_read_b128 v[202:205], v181 offset:52224
	ds_read_b128 v[206:209], v181 offset:53248
	ds_read_b128 v[210:213], v181 offset:54272
	ds_read_b128 v[214:217], v181 offset:55296
	ds_read_b128 v[224:227], v181 offset:56320
	global_load_lds_dwordx4 v[176:177], off
	s_add_i32 m0, s30, 0x2000
	s_add_u32 s28, s28, 0x80080
	v_lshl_add_u64 v[176:177], v[218:219], 0, s[64:65]
	s_addc_u32 s29, s29, 0
	s_add_i32 s30, s91, s42
	global_load_lds_dwordx4 v[176:177], off
	s_mov_b32 m0, s30
	v_lshl_add_u64 v[176:177], s[28:29], 0, v[0:1]
	global_load_lds_dwordx4 v[176:177], off
	s_add_i32 m0, s30, 0x2000
	v_lshl_add_u64 v[176:177], s[28:29], 0, v[126:127]
	global_load_lds_dwordx4 v[176:177], off
	s_mov_b32 m0, s86
	v_lshl_add_u64 v[176:177], v[220:221], 0, s[64:65]
	global_load_lds_dwordx4 v[176:177], off
	s_mov_b32 m0, s87
	v_lshl_add_u64 v[176:177], v[222:223], 0, s[64:65]
	global_load_lds_dwordx4 v[176:177], off
	s_waitcnt vmcnt(8) lgkmcnt(0)
	s_setprio 1
	s_barrier
	v_mfma_f32_16x16x32_bf16 v[62:65], v[152:155], v[190:193], v[62:65]
	v_mfma_f32_16x16x32_bf16 v[58:61], v[160:163], v[190:193], v[58:61]
	v_mfma_f32_16x16x32_bf16 v[46:49], v[152:155], v[198:201], v[46:49]
	v_mfma_f32_16x16x32_bf16 v[42:45], v[160:163], v[198:201], v[42:45]
	v_mfma_f32_16x16x32_bf16 v[30:33], v[152:155], v[206:209], v[30:33]
	v_mfma_f32_16x16x32_bf16 v[26:29], v[160:163], v[206:209], v[26:29]
	v_mfma_f32_16x16x32_bf16 v[14:17], v[152:155], v[214:217], v[14:17]
	v_mfma_f32_16x16x32_bf16 v[10:13], v[160:163], v[214:217], v[10:13]
	v_mfma_f32_16x16x32_bf16 v[62:65], v[156:159], v[194:197], v[62:65]
	v_mfma_f32_16x16x32_bf16 v[58:61], v[164:167], v[194:197], v[58:61]
	v_mfma_f32_16x16x32_bf16 v[46:49], v[156:159], v[202:205], v[46:49]
	v_mfma_f32_16x16x32_bf16 v[42:45], v[164:167], v[202:205], v[42:45]
	v_mfma_f32_16x16x32_bf16 v[30:33], v[156:159], v[210:213], v[30:33]
	v_mfma_f32_16x16x32_bf16 v[26:29], v[164:167], v[210:213], v[26:29]
	v_mfma_f32_16x16x32_bf16 v[14:17], v[156:159], v[224:227], v[14:17]
	v_mfma_f32_16x16x32_bf16 v[10:13], v[164:167], v[224:227], v[10:13]
	v_mfma_f32_16x16x32_bf16 v[54:57], v[168:171], v[190:193], v[54:57]
	v_mfma_f32_16x16x32_bf16 v[50:53], v[182:185], v[190:193], v[50:53]
	v_mfma_f32_16x16x32_bf16 v[38:41], v[168:171], v[198:201], v[38:41]
	v_mfma_f32_16x16x32_bf16 v[34:37], v[182:185], v[198:201], v[34:37]
	v_mfma_f32_16x16x32_bf16 v[22:25], v[168:171], v[206:209], v[22:25]
	v_mfma_f32_16x16x32_bf16 v[18:21], v[182:185], v[206:209], v[18:21]
	v_mfma_f32_16x16x32_bf16 v[6:9], v[168:171], v[214:217], v[6:9]
	v_mfma_f32_16x16x32_bf16 v[2:5], v[182:185], v[214:217], v[2:5]
	v_mfma_f32_16x16x32_bf16 v[54:57], v[172:175], v[194:197], v[54:57]
	v_mfma_f32_16x16x32_bf16 v[50:53], v[186:189], v[194:197], v[50:53]
	v_mfma_f32_16x16x32_bf16 v[38:41], v[172:175], v[202:205], v[38:41]
	v_mfma_f32_16x16x32_bf16 v[34:37], v[186:189], v[202:205], v[34:37]
	v_mfma_f32_16x16x32_bf16 v[22:25], v[172:175], v[210:213], v[22:25]
	v_mfma_f32_16x16x32_bf16 v[18:21], v[186:189], v[210:213], v[18:21]
	v_mfma_f32_16x16x32_bf16 v[6:9], v[172:175], v[224:227], v[6:9]
	v_mfma_f32_16x16x32_bf16 v[2:5], v[186:189], v[224:227], v[2:5]
	s_barrier
	s_setprio 0
	s_add_i32 s81, s81, 2
	s_add_u32 s0, s0, 0x100
	s_addc_u32 s1, s1, 0
	s_add_u32 s41, s41, 0x100
	s_addc_u32 s67, s67, 0
	s_cmp_gt_u32 s81, 29
	s_cbranch_scc0 .LBB0_910
	s_and_b64 vcc, exec, s[18:19]
	s_cbranch_vccz .LBB0_913
	s_barrier

; #define PG8_STAGE(bufoff, gbase, voff) do { _Pragma("unroll") for (int _i = 0; _i < 2; ++_i) \
;         __builtin_amdgcn_global_load_lds((const unsigned*)((const char*)(gbase) + (voff)[_i]), (PG8_LAS unsigned*)(lds + (bufoff) + ldsw + _i * 8192), 16, 0, 0); } while (0)
; #define PG8_LDA(dst, b, h) do { _Pragma("unroll") for (int m = 0; m < 4; ++m) _Pragma("unroll") for (int k = 0; k < 2; ++k) dst[m][k] = *(const PG8_LAS bf16x8*)(lds + PG8_SA(b, h) + aoff + m * 2048 + k * 1024); } while (0)
; #define PG8_LDB(dst, b, h) do { _Pragma("unroll") for (int n = 0; n < 2; ++n) _Pragma("unroll") for (int k = 0; k < 2; ++k) dst[n][k] = *(const PG8_LAS bf16x8*)(lds + PG8_SB(b, h) + boff + n * 2048 + k * 1024); } while (0)
; #define PG8_BAR __builtin_amdgcn_s_barrier()
; template <class Epi, class Sched, bool ALIGN_EPI = false, bool SP2 = false>
; __device__ __forceinline__ void gemm_phase(PG8_LAS unsigned char* lds, const Gemm g, const Sched& S, const Epi& E) {
;     ...
;             const bool last = (t == nt - 2);
;             const char* a1 = cA + (size_t)(t + 1) * kstep;
;             const char* a2 = last ? nA : cA + (size_t)(t + 2) * kstep; const char* b2 = last ? nB : cB + (size_t)(t + 2) * kstep;
;             const char* a3 = a2 + kstep; const char* b3 = b2 + kstep;
;             if (last && has_next) S.a_ready(nxt);
;             if constexpr (SP2) {
;             PG8_LDB(B0, 0, 0); PG8_LDB(B1, 0, 1); PG8_SCHED; PG8_LDA(At, 0, 0); PG8_STAGE(PG8_SA(1, 1), a1 + hstep, voffA);
;             PG8_WAIT_V(8); PG8_WAIT_L(0); PG8_BAR; PG8_MMA(0, 0, At, B0); PG8_MMA(0, 1, At, B1); PG8_BAR; PG8_SCHED;
;             PG8_LDA(At, 0, 1); PG8_STAGE(PG8_SB(0, 0), b2, voffB); PG8_STAGE(PG8_SB(0, 1), b2 + hstep, voffB); PG8_STAGE(PG8_SA(0, 0), a2, voffA);
;             PG8_WAIT_V(8); PG8_WAIT_L(0); PG8_BAR; PG8_MMA(1, 0, At, B0); PG8_MMA(1, 1, At, B1); PG8_BAR; PG8_SCHED;
;             PG8_LDB(B0, 1, 0); PG8_LDB(B1, 1, 1); PG8_SCHED; PG8_LDA(At, 1, 0); PG8_STAGE(PG8_SA(0, 1), a2 + hstep, voffA);
;             PG8_WAIT_V(8); PG8_WAIT_L(0); PG8_BAR; PG8_MMA(0, 0, At, B0); PG8_MMA(0, 1, At, B1); PG8_BAR; PG8_SCHED;
;             PG8_LDA(At, 1, 1); PG8_STAGE(PG8_SB(1, 0), b3, voffB); PG8_STAGE(PG8_SB(1, 1), b3 + hstep, voffB); PG8_STAGE(PG8_SA(1, 0), a3, voffA);
;             PG8_WAIT_V(8); PG8_WAIT_L(0); PG8_BAR; PG8_MMA(1, 0, At, B0); PG8_MMA(1, 1, At, B1); PG8_BAR; PG8_SCHED;
.LBB0_963:
	s_add_u32 s24, s0, 0xfff80080
	s_addc_u32 s25, s1, -1
	s_add_i32 s43, 0, 0x10000
	s_cmp_eq_u32 s42, 28
	s_cselect_b32 s27, s13, s25
	s_cselect_b32 s26, s17, s24
	s_cselect_b32 s25, s19, s41
	s_cselect_b32 s24, s29, s40
	s_add_i32 s48, 0, 0x14000
	v_add_u32_e32 v164, s43, v197
	v_add_u32_e32 v180, s48, v197
	ds_read_b128 v[152:155], v164
	ds_read_b128 v[156:159], v164 offset:1024
	ds_read_b128 v[160:163], v164 offset:2048
	ds_read_b128 v[164:167], v164 offset:3072
	ds_read_b128 v[168:171], v180
	ds_read_b128 v[172:175], v180 offset:1024
	ds_read_b128 v[176:179], v180 offset:2048
	ds_read_b128 v[180:183], v180 offset:3072
	v_lshl_add_u64 v[220:221], s[0:1], 0, v[148:149]
	s_add_i32 m0, s31, 0xc000
	ds_read_b128 v[184:187], v199
	ds_read_b128 v[188:191], v199 offset:1024
	ds_read_b128 v[192:195], v199 offset:2048
	ds_read_b128 v[200:203], v199 offset:3072
	ds_read_b128 v[204:207], v199 offset:4096
	ds_read_b128 v[208:211], v199 offset:5120
	ds_read_b128 v[212:215], v199 offset:6144
	ds_read_b128 v[216:219], v199 offset:7168
	global_load_lds_dwordx4 v[220:221], off
	s_add_i32 m0, s31, 0xe000
	v_lshl_add_u64 v[220:221], s[0:1], 0, v[150:151]
	global_load_lds_dwordx4 v[220:221], off
	s_waitcnt vmcnt(8) lgkmcnt(0)
	s_setprio 1
	s_barrier
	v_mfma_f32_16x16x32_bf16 v[144:147], v[152:155], v[184:187], v[144:147]
	v_mfma_f32_16x16x32_bf16 v[122:125], v[160:163], v[184:187], v[122:125]
	v_mfma_f32_16x16x32_bf16 v[110:113], v[152:155], v[192:195], v[110:113]
	v_mfma_f32_16x16x32_bf16 v[106:109], v[160:163], v[192:195], v[106:109]
	v_mfma_f32_16x16x32_bf16 v[94:97], v[152:155], v[204:207], v[94:97]
	v_mfma_f32_16x16x32_bf16 v[90:93], v[160:163], v[204:207], v[90:93]
	v_mfma_f32_16x16x32_bf16 v[78:81], v[152:155], v[212:215], v[78:81]
	v_mfma_f32_16x16x32_bf16 v[74:77], v[160:163], v[212:215], v[74:77]
	v_mfma_f32_16x16x32_bf16 v[144:147], v[156:159], v[188:191], v[144:147]
	v_mfma_f32_16x16x32_bf16 v[122:125], v[164:167], v[188:191], v[122:125]
	v_mfma_f32_16x16x32_bf16 v[110:113], v[156:159], v[200:203], v[110:113]
	v_mfma_f32_16x16x32_bf16 v[106:109], v[164:167], v[200:203], v[106:109]
	v_mfma_f32_16x16x32_bf16 v[94:97], v[156:159], v[208:211], v[94:97]
	v_mfma_f32_16x16x32_bf16 v[90:93], v[164:167], v[208:211], v[90:93]
	v_mfma_f32_16x16x32_bf16 v[78:81], v[156:159], v[216:219], v[78:81]
	v_mfma_f32_16x16x32_bf16 v[74:77], v[164:167], v[216:219], v[74:77]
	v_mfma_f32_16x16x32_bf16 v[118:121], v[168:171], v[184:187], v[118:121]
	v_mfma_f32_16x16x32_bf16 v[114:117], v[176:179], v[184:187], v[114:117]
	v_mfma_f32_16x16x32_bf16 v[102:105], v[168:171], v[192:195], v[102:105]
	v_mfma_f32_16x16x32_bf16 v[98:101], v[176:179], v[192:195], v[98:101]
	v_mfma_f32_16x16x32_bf16 v[86:89], v[168:171], v[204:207], v[86:89]
	v_mfma_f32_16x16x32_bf16 v[82:85], v[176:179], v[204:207], v[82:85]
	v_mfma_f32_16x16x32_bf16 v[70:73], v[168:171], v[212:215], v[70:73]
	v_mfma_f32_16x16x32_bf16 v[66:69], v[176:179], v[212:215], v[66:69]
	v_mfma_f32_16x16x32_bf16 v[118:121], v[172:175], v[188:191], v[118:121]
	v_mfma_f32_16x16x32_bf16 v[114:117], v[180:183], v[188:191], v[114:117]
	v_mfma_f32_16x16x32_bf16 v[102:105], v[172:175], v[200:203], v[102:105]
	v_mfma_f32_16x16x32_bf16 v[98:101], v[180:183], v[200:203], v[98:101]
	v_mfma_f32_16x16x32_bf16 v[86:89], v[172:175], v[208:211], v[86:89]
	v_mfma_f32_16x16x32_bf16 v[82:85], v[180:183], v[208:211], v[82:85]
	v_mfma_f32_16x16x32_bf16 v[70:73], v[172:175], v[216:219], v[70:73]
	v_mfma_f32_16x16x32_bf16 v[66:69], v[180:183], v[216:219], v[66:69]
	s_barrier
	s_setprio 0
	s_add_i32 s43, s43, s30
	v_lshl_add_u64 v[220:221], s[24:25], 0, v[0:1]
	s_mov_b32 m0, s43
	ds_read_b128 v[184:187], v199 offset:16384
	ds_read_b128 v[188:191], v199 offset:17408
	ds_read_b128 v[192:195], v199 offset:18432
	ds_read_b128 v[200:203], v199 offset:19456
	ds_read_b128 v[204:207], v199 offset:20480
	ds_read_b128 v[208:211], v199 offset:21504
	ds_read_b128 v[212:215], v199 offset:22528
	ds_read_b128 v[216:219], v199 offset:23552
	global_load_lds_dwordx4 v[220:221], off
	s_add_i32 m0, s43, 0x2000
	s_add_u32 vcc_lo, s24, 0x80000
	v_lshl_add_u64 v[222:223], s[24:25], 0, v[126:127]
	s_addc_u32 vcc_hi, s25, 0
	s_add_i32 s43, s48, s30
	global_load_lds_dwordx4 v[222:223], off
	v_lshl_add_u64 v[224:225], vcc, 0, v[0:1]
	s_mov_b32 m0, s43
	v_lshl_add_u64 v[226:227], s[26:27], 0, v[126:127]
	global_load_lds_dwordx4 v[224:225], off
	s_add_i32 m0, s43, 0x2000
	v_lshl_add_u64 v[224:225], vcc, 0, v[126:127]
	global_load_lds_dwordx4 v[224:225], off
	s_mov_b32 m0, s31
	v_lshl_add_u64 v[224:225], s[26:27], 0, v[0:1]
	global_load_lds_dwordx4 v[224:225], off
	s_mov_b32 m0, s34
	s_nop 0
	global_load_lds_dwordx4 v[226:227], off
	s_waitcnt vmcnt(8) lgkmcnt(0)
	s_setprio 1
	s_barrier
; #define PG8_STAGE(bufoff, gbase, voff) do { _Pragma("unroll") for (int _i = 0; _i < 2; ++_i) \
;         __builtin_amdgcn_global_load_lds((const unsigned*)((const char*)(gbase) + (voff)[_i]), (PG8_LAS unsigned*)(lds + (bufoff) + ldsw + _i * 8192), 16, 0, 0); } while (0)
; #define PG8_LDA(dst, b, h) do { _Pragma("unroll") for (int m = 0; m < 4; ++m) _Pragma("unroll") for (int k = 0; k < 2; ++k) dst[m][k] = *(const PG8_LAS bf16x8*)(lds + PG8_SA(b, h) + aoff + m * 2048 + k * 1024); } while (0)
; #define PG8_LDB(dst, b, h) do { _Pragma("unroll") for (int n = 0; n < 2; ++n) _Pragma("unroll") for (int k = 0; k < 2; ++k) dst[n][k] = *(const PG8_LAS bf16x8*)(lds + PG8_SB(b, h) + boff + n * 2048 + k * 1024); } while (0)
; #define PG8_MMA(ai, bj, At, Bt) do { __builtin_amdgcn_s_setprio(1); _Pragma("unroll") for (int m = 0; m < 4; ++m) _Pragma("unroll") for (int n = 0; n < 2; ++n) _Pragma("unroll") for (int k = 0; k < 2; ++k) \
;         acc[ai][bj][m][n] = __builtin_amdgcn_mfma_f32_16x16x32_bf16(Bt[n][k], At[m][k], acc[ai][bj][m][n], 0, 0, 0); __builtin_amdgcn_s_setprio(0); } while (0)
; #define PG8_WAIT_V(n) asm volatile("s_waitcnt vmcnt(" #n ")" ::: "memory")
; #define PG8_WAIT_L(n) asm volatile("s_waitcnt lgkmcnt(" #n ")" ::: "memory")
; #define PG8_BAR __builtin_amdgcn_s_barrier()
; #define PG8_SCHED __builtin_amdgcn_sched_barrier(0)
; template <class Epi, class Sched, bool ALIGN_EPI = false, bool SP2 = false>
; __device__ __forceinline__ void gemm_phase(PG8_LAS unsigned char* lds, const Gemm g, const Sched& S, const Epi& E) {
;     ...
;             PG8_WAIT_V(8); PG8_WAIT_L(0); PG8_BAR; PG8_MMA(0, 0, At, B0); PG8_MMA(0, 1, At, B1); PG8_BAR; PG8_SCHED;
;             PG8_LDA(At, 0, 1); PG8_STAGE(PG8_SB(0, 0), b2, voffB); PG8_STAGE(PG8_SB(0, 1), b2 + hstep, voffB); PG8_STAGE(PG8_SA(0, 0), a2, voffA);
;             PG8_WAIT_V(8); PG8_WAIT_L(0); PG8_BAR; PG8_MMA(1, 0, At, B0); PG8_MMA(1, 1, At, B1); PG8_BAR; PG8_SCHED;
;             PG8_LDB(B0, 1, 0); PG8_LDB(B1, 1, 1); PG8_SCHED; PG8_LDA(At, 1, 0); PG8_STAGE(PG8_SA(0, 1), a2 + hstep, voffA);
;             PG8_WAIT_V(8); PG8_WAIT_L(0); PG8_BAR; PG8_MMA(0, 0, At, B0); PG8_MMA(0, 1, At, B1); PG8_BAR; PG8_SCHED;
	v_mfma_f32_16x16x32_bf16 v[62:65], v[152:155], v[184:187], v[62:65]
	v_mfma_f32_16x16x32_bf16 v[58:61], v[160:163], v[184:187], v[58:61]
	v_mfma_f32_16x16x32_bf16 v[46:49], v[152:155], v[192:195], v[46:49]
	v_mfma_f32_16x16x32_bf16 v[42:45], v[160:163], v[192:195], v[42:45]
	v_mfma_f32_16x16x32_bf16 v[30:33], v[152:155], v[204:207], v[30:33]
	v_mfma_f32_16x16x32_bf16 v[26:29], v[160:163], v[204:207], v[26:29]
	v_mfma_f32_16x16x32_bf16 v[14:17], v[152:155], v[212:215], v[14:17]
	v_mfma_f32_16x16x32_bf16 v[10:13], v[160:163], v[212:215], v[10:13]
	v_mfma_f32_16x16x32_bf16 v[62:65], v[156:159], v[188:191], v[62:65]
	v_mfma_f32_16x16x32_bf16 v[58:61], v[164:167], v[188:191], v[58:61]
	v_mfma_f32_16x16x32_bf16 v[46:49], v[156:159], v[200:203], v[46:49]
	v_mfma_f32_16x16x32_bf16 v[42:45], v[164:167], v[200:203], v[42:45]
	v_mfma_f32_16x16x32_bf16 v[30:33], v[156:159], v[208:211], v[30:33]
	v_mfma_f32_16x16x32_bf16 v[26:29], v[164:167], v[208:211], v[26:29]
	v_mfma_f32_16x16x32_bf16 v[14:17], v[156:159], v[216:219], v[14:17]
	v_mfma_f32_16x16x32_bf16 v[10:13], v[164:167], v[216:219], v[10:13]
	v_mfma_f32_16x16x32_bf16 v[54:57], v[168:171], v[184:187], v[54:57]
	v_mfma_f32_16x16x32_bf16 v[50:53], v[176:179], v[184:187], v[50:53]
	v_mfma_f32_16x16x32_bf16 v[38:41], v[168:171], v[192:195], v[38:41]
	v_mfma_f32_16x16x32_bf16 v[34:37], v[176:179], v[192:195], v[34:37]
	v_mfma_f32_16x16x32_bf16 v[22:25], v[168:171], v[204:207], v[22:25]
	v_mfma_f32_16x16x32_bf16 v[18:21], v[176:179], v[204:207], v[18:21]
	v_mfma_f32_16x16x32_bf16 v[6:9], v[168:171], v[212:215], v[6:9]
	v_mfma_f32_16x16x32_bf16 v[2:5], v[176:179], v[212:215], v[2:5]
	v_mfma_f32_16x16x32_bf16 v[54:57], v[172:175], v[188:191], v[54:57]
	v_mfma_f32_16x16x32_bf16 v[50:53], v[180:183], v[188:191], v[50:53]
	v_mfma_f32_16x16x32_bf16 v[38:41], v[172:175], v[200:203], v[38:41]
	v_mfma_f32_16x16x32_bf16 v[34:37], v[180:183], v[200:203], v[34:37]
	v_mfma_f32_16x16x32_bf16 v[22:25], v[172:175], v[208:211], v[22:25]
	v_mfma_f32_16x16x32_bf16 v[18:21], v[180:183], v[208:211], v[18:21]
	v_mfma_f32_16x16x32_bf16 v[6:9], v[172:175], v[216:219], v[6:9]
	v_mfma_f32_16x16x32_bf16 v[2:5], v[180:183], v[216:219], v[2:5]
	s_barrier
	s_setprio 0
	s_add_i32 s43, 0, 0x18000
	s_add_i32 s48, 0, 0x1c000
	v_add_u32_e32 v164, s43, v197
	v_add_u32_e32 v180, s48, v197
	ds_read_b128 v[152:155], v164
	ds_read_b128 v[156:159], v164 offset:1024
	ds_read_b128 v[160:163], v164 offset:2048
	ds_read_b128 v[164:167], v164 offset:3072
	ds_read_b128 v[168:171], v180
	ds_read_b128 v[172:175], v180 offset:1024
	ds_read_b128 v[176:179], v180 offset:2048
	ds_read_b128 v[180:183], v180 offset:3072
	s_add_u32 s26, s26, 0x80000
	s_addc_u32 s27, s27, 0
	s_mov_b32 m0, s35
	v_lshl_add_u64 v[228:229], s[26:27], 0, v[0:1]
	ds_read_b128 v[184:187], v199 offset:32768
	ds_read_b128 v[188:191], v199 offset:33792
	ds_read_b128 v[192:195], v199 offset:34816
	ds_read_b128 v[200:203], v199 offset:35840
	ds_read_b128 v[204:207], v199 offset:36864
	ds_read_b128 v[208:211], v199 offset:37888
	ds_read_b128 v[212:215], v199 offset:38912
	ds_read_b128 v[216:219], v199 offset:39936
	global_load_lds_dwordx4 v[228:229], off
	s_mov_b32 m0, s76
	v_lshl_add_u64 v[228:229], s[26:27], 0, v[126:127]
	global_load_lds_dwordx4 v[228:229], off
	s_waitcnt vmcnt(8) lgkmcnt(0)
	s_setprio 1
	s_barrier
	v_mfma_f32_16x16x32_bf16 v[144:147], v[152:155], v[184:187], v[144:147]
	v_mfma_f32_16x16x32_bf16 v[122:125], v[160:163], v[184:187], v[122:125]
	v_mfma_f32_16x16x32_bf16 v[110:113], v[152:155], v[192:195], v[110:113]
	v_mfma_f32_16x16x32_bf16 v[106:109], v[160:163], v[192:195], v[106:109]
	v_mfma_f32_16x16x32_bf16 v[94:97], v[152:155], v[204:207], v[94:97]
	v_mfma_f32_16x16x32_bf16 v[90:93], v[160:163], v[204:207], v[90:93]
	v_mfma_f32_16x16x32_bf16 v[78:81], v[152:155], v[212:215], v[78:81]
	v_mfma_f32_16x16x32_bf16 v[74:77], v[160:163], v[212:215], v[74:77]
	v_mfma_f32_16x16x32_bf16 v[144:147], v[156:159], v[188:191], v[144:147]
	v_mfma_f32_16x16x32_bf16 v[122:125], v[164:167], v[188:191], v[122:125]
	v_mfma_f32_16x16x32_bf16 v[110:113], v[156:159], v[200:203], v[110:113]
	v_mfma_f32_16x16x32_bf16 v[106:109], v[164:167], v[200:203], v[106:109]
	v_mfma_f32_16x16x32_bf16 v[94:97], v[156:159], v[208:211], v[94:97]
	v_mfma_f32_16x16x32_bf16 v[90:93], v[164:167], v[208:211], v[90:93]
	v_mfma_f32_16x16x32_bf16 v[78:81], v[156:159], v[216:219], v[78:81]
	v_mfma_f32_16x16x32_bf16 v[74:77], v[164:167], v[216:219], v[74:77]
	v_mfma_f32_16x16x32_bf16 v[118:121], v[168:171], v[184:187], v[118:121]
	v_mfma_f32_16x16x32_bf16 v[114:117], v[176:179], v[184:187], v[114:117]
	v_mfma_f32_16x16x32_bf16 v[102:105], v[168:171], v[192:195], v[102:105]
	v_mfma_f32_16x16x32_bf16 v[98:101], v[176:179], v[192:195], v[98:101]
	v_mfma_f32_16x16x32_bf16 v[86:89], v[168:171], v[204:207], v[86:89]
	v_mfma_f32_16x16x32_bf16 v[82:85], v[176:179], v[204:207], v[82:85]
	v_mfma_f32_16x16x32_bf16 v[70:73], v[168:171], v[212:215], v[70:73]
	v_mfma_f32_16x16x32_bf16 v[66:69], v[176:179], v[212:215], v[66:69]
	v_mfma_f32_16x16x32_bf16 v[118:121], v[172:175], v[188:191], v[118:121]
	v_mfma_f32_16x16x32_bf16 v[114:117], v[180:183], v[188:191], v[114:117]
	v_mfma_f32_16x16x32_bf16 v[102:105], v[172:175], v[200:203], v[102:105]
	v_mfma_f32_16x16x32_bf16 v[98:101], v[180:183], v[200:203], v[98:101]
	v_mfma_f32_16x16x32_bf16 v[86:89], v[172:175], v[208:211], v[86:89]
	v_mfma_f32_16x16x32_bf16 v[82:85], v[180:183], v[208:211], v[82:85]
	v_mfma_f32_16x16x32_bf16 v[70:73], v[172:175], v[216:219], v[70:73]
	v_mfma_f32_16x16x32_bf16 v[66:69], v[180:183], v[216:219], v[66:69]
	s_barrier
; #define PG8_STAGE(bufoff, gbase, voff) do { _Pragma("unroll") for (int _i = 0; _i < 2; ++_i) \
;         __builtin_amdgcn_global_load_lds((const unsigned*)((const char*)(gbase) + (voff)[_i]), (PG8_LAS unsigned*)(lds + (bufoff) + ldsw + _i * 8192), 16, 0, 0); } while (0)
; #define PG8_LDA(dst, b, h) do { _Pragma("unroll") for (int m = 0; m < 4; ++m) _Pragma("unroll") for (int k = 0; k < 2; ++k) dst[m][k] = *(const PG8_LAS bf16x8*)(lds + PG8_SA(b, h) + aoff + m * 2048 + k * 1024); } while (0)
; #define PG8_WAIT_V(n) asm volatile("s_waitcnt vmcnt(" #n ")" ::: "memory")
; template <class Epi, class Sched, bool ALIGN_EPI = false, bool SP2 = false>
; __device__ __forceinline__ void gemm_phase(PG8_LAS unsigned char* lds, const Gemm g, const Sched& S, const Epi& E) {
;     ...
;         for (int t = 0; t < nt; t += 2) {
;             if constexpr (Epi::HAS_MID) { if (t == Epi::MID0 || t == Epi::MID1) E.mid(acc, cur, wr, wc, fr, fq, t == Epi::MID0 ? 0 : 1); }
;             const bool last = (t == nt - 2);
;             const char* a1 = cA + (size_t)(t + 1) * kstep;
;             const char* a2 = last ? nA : cA + (size_t)(t + 2) * kstep; const char* b2 = last ? nB : cB + (size_t)(t + 2) * kstep;
;             const char* a3 = a2 + kstep; const char* b3 = b2 + kstep;
;             if (last && has_next) S.a_ready(nxt);
;             if constexpr (SP2) {
;             PG8_LDB(B0, 0, 0); PG8_LDB(B1, 0, 1); PG8_SCHED; PG8_LDA(At, 0, 0); PG8_STAGE(PG8_SA(1, 1), a1 + hstep, voffA);
;             PG8_WAIT_V(8); PG8_WAIT_L(0); PG8_BAR; PG8_MMA(0, 0, At, B0); PG8_MMA(0, 1, At, B1); PG8_BAR; PG8_SCHED;
;             PG8_LDA(At, 0, 1); PG8_STAGE(PG8_SB(0, 0), b2, voffB); PG8_STAGE(PG8_SB(0, 1), b2 + hstep, voffB); PG8_STAGE(PG8_SA(0, 0), a2, voffA);
;             PG8_WAIT_V(8); PG8_WAIT_L(0); PG8_BAR; PG8_MMA(1, 0, At, B0); PG8_MMA(1, 1, At, B1); PG8_BAR; PG8_SCHED;
;             PG8_LDB(B0, 1, 0); PG8_LDB(B1, 1, 1); PG8_SCHED; PG8_LDA(At, 1, 0); PG8_STAGE(PG8_SA(0, 1), a2 + hstep, voffA);
;             PG8_WAIT_V(8); PG8_WAIT_L(0); PG8_BAR; PG8_MMA(0, 0, At, B0); PG8_MMA(0, 1, At, B1); PG8_BAR; PG8_SCHED;
;             PG8_LDA(At, 1, 1); PG8_STAGE(PG8_SB(1, 0), b3, voffB); PG8_STAGE(PG8_SB(1, 1), b3 + hstep, voffB); PG8_STAGE(PG8_SA(1, 0), a3, voffA);
;             PG8_WAIT_V(8); PG8_WAIT_L(0); PG8_BAR; PG8_MMA(1, 0, At, B0); PG8_MMA(1, 1, At, B1); PG8_BAR; PG8_SCHED;
	s_setprio 0
	s_add_i32 s26, s43, s30
	v_lshl_add_u64 v[220:221], v[220:221], 0, s[64:65]
	s_mov_b32 m0, s26
	ds_read_b128 v[184:187], v199 offset:49152
	ds_read_b128 v[188:191], v199 offset:50176
	ds_read_b128 v[192:195], v199 offset:51200
	ds_read_b128 v[200:203], v199 offset:52224
	ds_read_b128 v[204:207], v199 offset:53248
	ds_read_b128 v[208:211], v199 offset:54272
	ds_read_b128 v[212:215], v199 offset:55296
	ds_read_b128 v[216:219], v199 offset:56320
	global_load_lds_dwordx4 v[220:221], off
	s_add_i32 m0, s26, 0x2000
	s_add_u32 s24, s24, 0x80080
	v_lshl_add_u64 v[220:221], v[222:223], 0, s[64:65]
	s_addc_u32 s25, s25, 0
	s_add_i32 s26, s48, s30
	global_load_lds_dwordx4 v[220:221], off
	s_mov_b32 m0, s26
	v_lshl_add_u64 v[220:221], s[24:25], 0, v[0:1]
	global_load_lds_dwordx4 v[220:221], off
	s_add_i32 m0, s26, 0x2000
	v_lshl_add_u64 v[220:221], s[24:25], 0, v[126:127]
	global_load_lds_dwordx4 v[220:221], off
	s_mov_b32 m0, s82
	v_lshl_add_u64 v[220:221], v[224:225], 0, s[64:65]
	global_load_lds_dwordx4 v[220:221], off
	s_mov_b32 m0, s83
	v_lshl_add_u64 v[220:221], v[226:227], 0, s[64:65]
	global_load_lds_dwordx4 v[220:221], off
	s_waitcnt vmcnt(8) lgkmcnt(0)
	s_setprio 1
	s_barrier
	v_mfma_f32_16x16x32_bf16 v[62:65], v[152:155], v[184:187], v[62:65]
	v_mfma_f32_16x16x32_bf16 v[58:61], v[160:163], v[184:187], v[58:61]
	v_mfma_f32_16x16x32_bf16 v[46:49], v[152:155], v[192:195], v[46:49]
	v_mfma_f32_16x16x32_bf16 v[42:45], v[160:163], v[192:195], v[42:45]
	v_mfma_f32_16x16x32_bf16 v[30:33], v[152:155], v[204:207], v[30:33]
	v_mfma_f32_16x16x32_bf16 v[26:29], v[160:163], v[204:207], v[26:29]
	v_mfma_f32_16x16x32_bf16 v[14:17], v[152:155], v[212:215], v[14:17]
	v_mfma_f32_16x16x32_bf16 v[10:13], v[160:163], v[212:215], v[10:13]
	v_mfma_f32_16x16x32_bf16 v[62:65], v[156:159], v[188:191], v[62:65]
	v_mfma_f32_16x16x32_bf16 v[58:61], v[164:167], v[188:191], v[58:61]
	v_mfma_f32_16x16x32_bf16 v[46:49], v[156:159], v[200:203], v[46:49]
	v_mfma_f32_16x16x32_bf16 v[42:45], v[164:167], v[200:203], v[42:45]
	v_mfma_f32_16x16x32_bf16 v[30:33], v[156:159], v[208:211], v[30:33]
	v_mfma_f32_16x16x32_bf16 v[26:29], v[164:167], v[208:211], v[26:29]
	v_mfma_f32_16x16x32_bf16 v[14:17], v[156:159], v[216:219], v[14:17]
	v_mfma_f32_16x16x32_bf16 v[10:13], v[164:167], v[216:219], v[10:13]
	v_mfma_f32_16x16x32_bf16 v[54:57], v[168:171], v[184:187], v[54:57]
	v_mfma_f32_16x16x32_bf16 v[50:53], v[176:179], v[184:187], v[50:53]
	v_mfma_f32_16x16x32_bf16 v[38:41], v[168:171], v[192:195], v[38:41]
	v_mfma_f32_16x16x32_bf16 v[34:37], v[176:179], v[192:195], v[34:37]
	v_mfma_f32_16x16x32_bf16 v[22:25], v[168:171], v[204:207], v[22:25]
	v_mfma_f32_16x16x32_bf16 v[18:21], v[176:179], v[204:207], v[18:21]
	v_mfma_f32_16x16x32_bf16 v[6:9], v[168:171], v[212:215], v[6:9]
	v_mfma_f32_16x16x32_bf16 v[2:5], v[176:179], v[212:215], v[2:5]
	v_mfma_f32_16x16x32_bf16 v[54:57], v[172:175], v[188:191], v[54:57]
	v_mfma_f32_16x16x32_bf16 v[50:53], v[180:183], v[188:191], v[50:53]
	v_mfma_f32_16x16x32_bf16 v[38:41], v[172:175], v[200:203], v[38:41]
	v_mfma_f32_16x16x32_bf16 v[34:37], v[180:183], v[200:203], v[34:37]
	v_mfma_f32_16x16x32_bf16 v[22:25], v[172:175], v[208:211], v[22:25]
	v_mfma_f32_16x16x32_bf16 v[18:21], v[180:183], v[208:211], v[18:21]
	v_mfma_f32_16x16x32_bf16 v[6:9], v[172:175], v[216:219], v[6:9]
	v_mfma_f32_16x16x32_bf16 v[2:5], v[180:183], v[216:219], v[2:5]
	s_barrier
	s_setprio 0
	s_add_i32 s42, s42, 2
	s_add_u32 s0, s0, 0x100
	s_addc_u32 s1, s1, 0
	s_add_u32 s40, s40, 0x100
	s_addc_u32 s41, s41, 0
	s_cmp_gt_u32 s42, 29
	s_cbranch_scc0 .LBB0_963
	s_and_b64 vcc, exec, s[14:15]
	s_cbranch_vccz .LBB0_966
	s_barrier
